# rowwise phases (x4): hoist loop-invariant post-norm gain loads out of the row loop so the next-row prefetch is no longer drained every iteration
# speedup vs baseline: 1.0285x; 1.0060x over previous
; __device__ __forceinline__ float bf_lo(unsigned w) { return __uint_as_float(w << 16); }
; __device__ __forceinline__ float bf_hi(unsigned w) { return __uint_as_float(w & 0xffff0000u); }
; template <int MODE>
; __device__ __forceinline__ void rowwise_phase(const float* xin, bf16_t* hb, const bf16_t* f, const float* gpost, float alpha, float* rsout, float* fout, int wg, int nwg, int row0, int rowend) {
;     ...
;     if (gw < rowend) ROW_LOAD(gw);
;     for (int row = gw; row < rowend; row += NGW) {
;         f32x4 h[8]; u32x2 fw[8];
; #pragma unroll
;         for (int j = 0; j < 8; ++j) { if (XIN) h[j] = xN[j]; else h[j] = (f32x4){bf_lo(hN[j].x), bf_hi(hN[j].x), bf_lo(hN[j].y), bf_hi(hN[j].y)}; if (HASF) fw[j] = fN[j]; }
;         const int nrow = row + NGW;
;         if (nrow < rowend) ROW_LOAD(nrow);
.LBB0_340:
	s_or_b64 exec, exec, s[4:5]
	v_readlane_b32 s3, v232, 9
	v_mov_b32_e32 v1, v158
	s_and_b32 s2, s2, -8
	s_waitcnt lgkmcnt(0)
	s_barrier
	v_writelane_b32 v232, s2, 22
	s_add_i32 s2, s3, s2
	v_ashrrev_i32_e32 v0, 6, v1
	s_add_i32 s13, s3, 0x800
	v_add_u32_e32 v0, s2, v0
	s_and_b32 s26, s67, -8
	v_cmp_gt_i32_e32 vcc, s13, v0
	v_writelane_b32 v232, s2, 23
	s_and_saveexec_b64 s[6:7], vcc
	s_cbranch_execz .LBB0_347
	v_and_b32_e32 v8, 63, v1
	v_ashrrev_i32_e32 v1, 31, v0
	v_readlane_b32 s40, v232, 16
	v_lshlrev_b64 v[2:3], 12, v[0:1]
	v_readlane_b32 s38, v232, 7
	v_readlane_b32 s41, v232, 17
	v_readlane_b32 s39, v232, 8
	v_lshlrev_b32_e32 v10, 3, v8
	v_mov_b32_e32 v11, 0
	v_lshl_add_u64 v[6:7], s[40:41], 0, v[2:3]
	v_lshl_add_u64 v[4:5], s[38:39], 0, v[2:3]
	v_lshl_add_u64 v[6:7], v[6:7], 0, v[10:11]
	v_lshl_add_u64 v[4:5], v[4:5], 0, v[10:11]
	global_load_dwordx2 v[86:87], v[6:7], off
	global_load_dwordx2 v[84:85], v[6:7], off offset:512
	global_load_dwordx2 v[82:83], v[6:7], off offset:1024
	global_load_dwordx2 v[80:81], v[6:7], off offset:1536
	global_load_dwordx2 v[72:73], v[6:7], off offset:2048
	global_load_dwordx2 v[70:71], v[6:7], off offset:2560
	global_load_dwordx2 v[68:69], v[6:7], off offset:3072
	global_load_dwordx2 v[66:67], v[6:7], off offset:3584
	global_load_dwordx2 v[74:75], v[4:5], off
	global_load_dwordx2 v[64:65], v[4:5], off offset:512
	global_load_dwordx2 v[62:63], v[4:5], off offset:1024
	global_load_dwordx2 v[60:61], v[4:5], off offset:1536
	global_load_dwordx2 v[58:59], v[4:5], off offset:2048
	global_load_dwordx2 v[56:57], v[4:5], off offset:2560
	global_load_dwordx2 v[54:55], v[4:5], off offset:3072
	global_load_dwordx2 v[52:53], v[4:5], off offset:3584
	v_mbcnt_hi_u32_b32 v14, -1, v159
	v_mov_b64_e32 v[4:5], 0xbb40000
	v_and_b32_e32 v15, 64, v14
	v_xor_b32_e32 v16, 1, v14
	v_lshl_add_u64 v[4:5], v[0:1], 2, v[4:5]
	v_add_u32_e32 v1, 64, v15
	v_xor_b32_e32 v17, 2, v14
	v_cmp_lt_i32_e32 vcc, v16, v1
	s_load_dwordx2 s[2:3], s[0:1], 0x30
	v_xor_b32_e32 v18, 4, v14
	v_cmp_eq_u32_e64 s[4:5], 0, v8
	v_lshlrev_b32_e32 v12, 4, v8
	v_lshl_add_u64 v[6:7], s[38:39], 0, v[10:11]
	v_lshl_add_u64 v[8:9], s[40:41], 0, v[10:11]
	v_or_b32_e32 v2, v2, v10
	v_cndmask_b32_e32 v10, v14, v16, vcc
	v_cmp_lt_i32_e32 vcc, v17, v1
	v_xor_b32_e32 v19, 8, v14
	v_mov_b32_e32 v13, v11
	v_cndmask_b32_e32 v11, v14, v17, vcc
	v_cmp_lt_i32_e32 vcc, v18, v1
	v_xor_b32_e32 v20, 16, v14
	v_xor_b32_e32 v21, 32, v14
	v_cndmask_b32_e32 v15, v14, v18, vcc
	v_cmp_lt_i32_e32 vcc, v19, v1
	s_mov_b64 s[10:11], 0x1000
	s_mov_b64 s[22:23], 0x1400
	v_cndmask_b32_e32 v16, v14, v19, vcc
	v_cmp_lt_i32_e32 vcc, v20, v1
	s_mov_b64 s[30:31], 0x1800
	s_mov_b64 s[36:37], 0x1c00
	v_cndmask_b32_e32 v17, v14, v20, vcc
	v_cmp_lt_i32_e32 vcc, v21, v1
	s_ashr_i32 s27, s26, 31
	v_lshlrev_b32_e32 v105, 2, v10
	v_cndmask_b32_e32 v1, v14, v21, vcc
	v_lshlrev_b32_e32 v106, 2, v11
	s_waitcnt lgkmcnt(0)
	v_lshl_add_u64 v[10:11], s[2:3], 0, v[12:13]
	s_mov_b64 s[8:9], 0
	v_mov_b32_e32 v104, 0x358637bd
	s_lshl_b64 s[28:29], s[26:27], 2
	s_lshl_b64 s[42:43], s[26:27], 12
	v_lshlrev_b32_e32 v107, 2, v15
	v_lshlrev_b32_e32 v108, 2, v16
	v_lshlrev_b32_e32 v109, 2, v17
	v_lshlrev_b32_e32 v110, 2, v1
	v_lshl_add_u64 v[12:13], v[10:11], 0, s[10:11]
	v_lshl_add_u64 v[14:15], v[10:11], 0, s[22:23]
	v_lshl_add_u64 v[16:17], v[10:11], 0, s[30:31]
	v_lshl_add_u64 v[18:19], v[10:11], 0, s[36:37]
	s_waitcnt vmcnt(15)
	v_mov_b64_e32 v[22:23], v[86:87]
	s_waitcnt vmcnt(14)
	v_mov_b64_e32 v[26:27], v[84:85]
	s_waitcnt vmcnt(13)
	v_mov_b64_e32 v[30:31], v[82:83]
	s_waitcnt vmcnt(12)
	v_mov_b64_e32 v[34:35], v[80:81]
	s_waitcnt vmcnt(11)
	v_mov_b64_e32 v[38:39], v[72:73]
	s_waitcnt vmcnt(10)
	v_mov_b64_e32 v[42:43], v[70:71]
	s_waitcnt vmcnt(9)
	v_mov_b64_e32 v[46:47], v[68:69]
	s_waitcnt vmcnt(8)
	v_mov_b64_e32 v[50:51], v[66:67]
	s_waitcnt vmcnt(7)
	v_mov_b64_e32 v[20:21], v[74:75]
	s_waitcnt vmcnt(6)
	v_mov_b64_e32 v[24:25], v[64:65]
	s_waitcnt vmcnt(5)
	v_mov_b64_e32 v[28:29], v[62:63]
	s_waitcnt vmcnt(4)
	v_mov_b64_e32 v[32:33], v[60:61]
	s_waitcnt vmcnt(3)
	v_mov_b64_e32 v[36:37], v[58:59]
	s_waitcnt vmcnt(2)
	v_mov_b64_e32 v[40:41], v[56:57]
	s_waitcnt vmcnt(1)
	v_mov_b64_e32 v[44:45], v[54:55]
	s_waitcnt vmcnt(0)
	v_mov_b64_e32 v[48:49], v[52:53]
	global_load_dwordx4 v[168:171], v[10:11], off
	global_load_dwordx4 v[172:175], v[10:11], off offset:1024
	global_load_dwordx4 v[176:179], v[10:11], off offset:2048
	global_load_dwordx4 v[180:183], v[10:11], off offset:3072
	global_load_dwordx4 v[184:187], v[12:13], off
	global_load_dwordx4 v[188:191], v[14:15], off
	global_load_dwordx4 v[192:195], v[16:17], off
	global_load_dwordx4 v[196:199], v[18:19], off
	s_waitcnt vmcnt(0)
	s_branch .LBB0_343
.LBB0_342:
	s_or_b64 exec, exec, s[2:3]
	s_waitcnt lgkmcnt(0)
	v_lshl_add_u64 v[70:71], s[16:17], 0, v[2:3]
	s_and_b64 s[2:3], exec, vcc
	v_add_co_u32_e32 v70, vcc, 0xbb50000, v70
	v_cvt_pk_bf16_f32 v72, v102, v103
	v_cvt_pk_bf16_f32 v73, v88, v89
	s_or_b64 s[8:9], s[2:3], s[8:9]
	s_nop 0
	v_addc_co_u32_e32 v71, vcc, 0, v71, vcc
	global_store_dwordx2 v[70:71], v[72:73], off
	v_cvt_pk_bf16_f32 v72, v86, v87
	v_cvt_pk_bf16_f32 v73, v84, v85
	global_store_dwordx2 v[70:71], v[72:73], off offset:512
	v_cvt_pk_bf16_f32 v72, v78, v79
	v_cvt_pk_bf16_f32 v73, v74, v75
	global_store_dwordx2 v[70:71], v[72:73], off offset:1024
	v_cvt_pk_bf16_f32 v72, v76, v77
	v_cvt_pk_bf16_f32 v73, v62, v63
	global_store_dwordx2 v[70:71], v[72:73], off offset:1536
	v_cvt_pk_bf16_f32 v62, v68, v69
	v_cvt_pk_bf16_f32 v63, v60, v61
	global_store_dwordx2 v[70:71], v[62:63], off offset:2048
	v_cvt_pk_bf16_f32 v60, v64, v65
	v_cvt_pk_bf16_f32 v61, v58, v59
	global_store_dwordx2 v[70:71], v[60:61], off offset:2560
	v_cvt_pk_bf16_f32 v56, v56, v57
	v_cvt_pk_bf16_f32 v57, v52, v53
	global_store_dwordx2 v[70:71], v[56:57], off offset:3072
	v_cvt_pk_bf16_f32 v52, v66, v67
	v_cvt_pk_bf16_f32 v53, v54, v55
	global_store_dwordx2 v[70:71], v[52:53], off offset:3584
	v_lshl_add_u64 v[4:5], v[4:5], 0, s[28:29]
	v_lshl_add_u64 v[2:3], v[2:3], 0, s[42:43]
	s_waitcnt vmcnt(9)
	v_mov_b64_e32 v[86:87], v[22:23]
	v_mov_b64_e32 v[84:85], v[26:27]
	v_mov_b64_e32 v[82:83], v[30:31]
	v_mov_b64_e32 v[80:81], v[34:35]
	v_mov_b64_e32 v[72:73], v[38:39]
	v_mov_b64_e32 v[70:71], v[42:43]
	v_mov_b64_e32 v[68:69], v[46:47]
	v_mov_b64_e32 v[66:67], v[50:51]
	v_mov_b64_e32 v[74:75], v[20:21]
	v_mov_b64_e32 v[64:65], v[24:25]
	v_mov_b64_e32 v[62:63], v[28:29]
	v_mov_b64_e32 v[60:61], v[32:33]
	v_mov_b64_e32 v[58:59], v[36:37]
	v_mov_b64_e32 v[56:57], v[40:41]
	v_mov_b64_e32 v[54:55], v[44:45]
	v_mov_b64_e32 v[52:53], v[48:49]
	s_andn2_b64 exec, exec, s[8:9]
	s_cbranch_execz .LBB0_347

; __device__ __forceinline__ float bf_lo(unsigned w) { return __uint_as_float(w << 16); }
; __device__ __forceinline__ float bf_hi(unsigned w) { return __uint_as_float(w & 0xffff0000u); }
; template <int MODE>
; __device__ __forceinline__ void rowwise_phase(const float* xin, bf16_t* hb, const bf16_t* f, const float* gpost, float alpha, float* rsout, float* fout, int wg, int nwg, int row0, int rowend) {
;     ...
;         if (HASF) {
;             f32x4 fv[8]; float ss = 0.f;
; #pragma unroll
;             for (int j = 0; j < 8; ++j) { const u32x2 w = fw[j]; fv[j] = (f32x4){bf_lo(w.x), bf_hi(w.x), bf_lo(w.y), bf_hi(w.y)};
;                 ss += (fv[j][0] * fv[j][0] + fv[j][1] * fv[j][1]) + (fv[j][2] * fv[j][2] + fv[j][3] * fv[j][3]); }
;             ss = wave_sum(ss);
;             const float rs = alpha * __frsqrt_rn(ss * (1.0f / DM) + EPS);
; #pragma unroll
;             for (int j = 0; j < 8; ++j) { const f32x4 g = ((const f32x4*)gpost)[lane + 64 * j]; h[j] += fv[j] * g * rs; }
.LBB0_345:
	s_or_b64 exec, exec, s[44:45]
	v_lshlrev_b32_e32 v88, 16, v86
	v_and_b32_e32 v89, 0xffff0000, v86
	v_lshlrev_b32_e32 v86, 16, v87
	v_and_b32_e32 v87, 0xffff0000, v87
	v_lshlrev_b32_e32 v76, 16, v74
	v_and_b32_e32 v77, 0xffff0000, v74
	v_lshlrev_b32_e32 v78, 16, v75
	v_and_b32_e32 v79, 0xffff0000, v75
	v_lshlrev_b32_e32 v74, 16, v64
	v_and_b32_e32 v75, 0xffff0000, v64
	v_mul_f32_e32 v64, v87, v87
	v_pk_fma_f32 v[98:99], v[86:87], v[86:87], v[64:65] op_sel_hi:[1,1,0]
	v_lshlrev_b32_e32 v91, 16, v85
	v_lshlrev_b32_e32 v90, 16, v84
	v_and_b32_e32 v85, 0xffff0000, v85
	v_and_b32_e32 v84, 0xffff0000, v84
	v_mul_f32_e32 v64, v89, v89
	v_pk_mul_f32 v[92:93], v[84:85], v[84:85]
	v_lshlrev_b32_e32 v97, 16, v80
	v_pk_fma_f32 v[102:103], v[88:89], v[88:89], v[64:65] op_sel_hi:[1,1,0]
	v_pk_fma_f32 v[100:101], v[90:91], v[90:91], v[92:93]
	v_and_b32_e32 v95, 0xffff0000, v80
	v_mov_b32_e32 v96, v102
	v_mov_b32_e32 v112, v98
	v_mov_b32_e32 v113, v97
	v_and_b32_e32 v93, 0xffff0000, v82
	v_mul_f32_e32 v1, v95, v95
	v_pk_add_f32 v[98:99], v[102:103], v[98:99]
	v_pk_mul_f32 v[102:103], v[96:97], v[112:113]
	v_pk_add_f32 v[100:101], v[100:101], v[100:101] op_sel:[0,1] op_sel_hi:[1,0]
	v_lshlrev_b32_e32 v92, 16, v82
	v_lshlrev_b32_e32 v82, 16, v83
	v_and_b32_e32 v83, 0xffff0000, v83
	v_mov_b32_e32 v99, v103
	v_mov_b32_e32 v101, v1
	v_mul_f32_e32 v64, v93, v93
	v_lshlrev_b32_e32 v80, 16, v81
	v_and_b32_e32 v81, 0xffff0000, v81
	v_pk_add_f32 v[98:99], v[98:99], v[100:101]
	v_pk_fma_f32 v[100:101], v[92:93], v[92:93], v[64:65] op_sel_hi:[1,1,0]
	v_mul_f32_e32 v64, v83, v83
	v_mul_f32_e32 v94, v80, v80
	v_mul_f32_e32 v111, v81, v81
	v_pk_fma_f32 v[102:103], v[82:83], v[82:83], v[64:65] op_sel_hi:[1,1,0]
	v_mov_b32_e32 v101, v94
	v_mov_b32_e32 v103, v111
	v_pk_add_f32 v[100:101], v[100:101], v[102:103]
	v_pk_add_f32 v[102:103], v[98:99], v[100:101]
	v_lshlrev_b32_e32 v99, 16, v73
	v_lshlrev_b32_e32 v98, 16, v72
	v_and_b32_e32 v73, 0xffff0000, v73
	v_and_b32_e32 v72, 0xffff0000, v72
	v_pk_mul_f32 v[100:101], v[72:73], v[72:73]
	v_lshlrev_b32_e32 v140, 16, v68
	v_pk_fma_f32 v[100:101], v[98:99], v[98:99], v[100:101]
	v_and_b32_e32 v141, 0xffff0000, v68
	v_pk_add_f32 v[124:125], v[100:101], v[100:101] op_sel:[0,1] op_sel_hi:[1,0]
	v_lshlrev_b32_e32 v101, 16, v71
	v_lshlrev_b32_e32 v100, 16, v70
	v_and_b32_e32 v71, 0xffff0000, v71
	v_and_b32_e32 v70, 0xffff0000, v70
	v_pk_mul_f32 v[116:117], v[70:71], v[70:71]
	v_lshlrev_b32_e32 v142, 16, v69
	v_pk_fma_f32 v[128:129], v[100:101], v[100:101], v[116:117]
	v_and_b32_e32 v143, 0xffff0000, v69
	v_lshlrev_b32_e32 v145, 16, v66
	v_and_b32_e32 v147, 0xffff0000, v66
	v_lshlrev_b32_e32 v148, 16, v67
	v_and_b32_e32 v149, 0xffff0000, v67
	v_pk_add_f32 v[102:103], v[102:103], v[102:103] op_sel:[0,1] op_sel_hi:[1,0]
	v_mov_b32_e32 v126, v124
	v_mov_b32_e32 v144, v102
	v_mov_b32_e32 v127, v145
	v_mul_f32_e32 v1, v147, v147
	v_pk_add_f32 v[102:103], v[102:103], v[124:125]
	v_pk_mul_f32 v[130:131], v[144:145], v[126:127]
	v_pk_add_f32 v[128:129], v[128:129], v[128:129] op_sel:[0,1] op_sel_hi:[1,0]
	v_mov_b32_e32 v103, v131
	v_mov_b32_e32 v129, v1
	v_pk_add_f32 v[102:103], v[102:103], v[128:129]
	v_mul_f32_e32 v64, v141, v141
	v_pk_fma_f32 v[136:137], v[140:141], v[140:141], v[64:65] op_sel_hi:[1,1,0]
	v_mul_f32_e32 v64, v143, v143
	v_mul_f32_e32 v94, v148, v148
	v_mul_f32_e32 v96, v149, v149
	v_pk_fma_f32 v[138:139], v[142:143], v[142:143], v[64:65] op_sel_hi:[1,1,0]
	v_mov_b32_e32 v137, v94
	v_mov_b32_e32 v139, v96
	v_pk_add_f32 v[136:137], v[136:137], v[138:139]
	v_lshlrev_b32_e32 v162, 16, v52
	v_pk_add_f32 v[102:103], v[102:103], v[136:137]
	v_add_f32_e32 v1, v102, v103
	ds_bpermute_b32 v94, v105, v1
	v_and_b32_e32 v163, 0xffff0000, v52
	v_lshlrev_b32_e32 v164, 16, v53
	v_and_b32_e32 v165, 0xffff0000, v53
	v_lshlrev_b32_e32 v150, 16, v62
	s_waitcnt lgkmcnt(0)
	v_add_f32_e32 v1, v1, v94
	ds_bpermute_b32 v94, v106, v1
	v_and_b32_e32 v151, 0xffff0000, v62
	v_lshlrev_b32_e32 v64, 16, v65
	v_and_b32_e32 v65, 0xffff0000, v65
	v_lshlrev_b32_e32 v152, 16, v60
	s_waitcnt lgkmcnt(0)
	v_add_f32_e32 v1, v1, v94
	ds_bpermute_b32 v94, v107, v1
	v_and_b32_e32 v153, 0xffff0000, v60
	v_lshlrev_b32_e32 v62, 16, v63
	v_and_b32_e32 v63, 0xffff0000, v63
	v_lshlrev_b32_e32 v60, 16, v61
	s_waitcnt lgkmcnt(0)
	v_add_f32_e32 v1, v1, v94
	ds_bpermute_b32 v94, v108, v1
	v_and_b32_e32 v61, 0xffff0000, v61
	v_lshlrev_b32_e32 v154, 16, v58
	v_and_b32_e32 v155, 0xffff0000, v58
	v_lshlrev_b32_e32 v58, 16, v59
	s_waitcnt lgkmcnt(0)
	v_add_f32_e32 v1, v1, v94
	ds_bpermute_b32 v94, v109, v1
	v_and_b32_e32 v59, 0xffff0000, v59
	v_lshlrev_b32_e32 v156, 16, v56
	v_pk_mul_f32 v[52:53], v[168:169], v[88:89]
	v_pk_mul_f32 v[86:87], v[170:171], v[86:87]
	s_waitcnt lgkmcnt(0)
; __device__ __forceinline__ unsigned cvt_pk_bf16(float lo, float hi) { unsigned r; asm volatile("v_cvt_pk_bf16_f32 %0, %1, %2" : "=v"(r) : "v"(lo), "v"(hi)); return r; }
; template <int MODE>
; __device__ __forceinline__ void rowwise_phase(const float* xin, bf16_t* hb, const bf16_t* f, const float* gpost, float alpha, float* rsout, float* fout, int wg, int nwg, int row0, int rowend) {
;     ...
;             ss = wave_sum(ss);
;             const float rs = alpha * __frsqrt_rn(ss * (1.0f / DM) + EPS);
; #pragma unroll
;             for (int j = 0; j < 8; ++j) { const f32x4 g = ((const f32x4*)gpost)[lane + 64 * j]; h[j] += fv[j] * g * rs; }
;         }
;         if (MODE == 2) {
;             f32x4* op = (f32x4*)(fout + (size_t)row * DM) + lane;
; #pragma unroll
;             for (int j = 0; j < 8; ++j) op[64 * j] = h[j];
;         } else {
;             float s2 = 0.f;
; #pragma unroll
;             for (int j = 0; j < 8; ++j) s2 += (h[j][0] * h[j][0] + h[j][1] * h[j][1]) + (h[j][2] * h[j][2] + h[j][3] * h[j][3]);
;             s2 = wave_sum(s2);
;             if (lane == 0) rsout[row] = __frsqrt_rn(s2 * (1.0f / DM) + EPS);
;             u32x2* up = (u32x2*)(hb + (size_t)row * DM) + lane;
; #pragma unroll
;             for (int j = 0; j < 8; ++j) { u32x2 w; w.x = cvt_pk_bf16(h[j][0], h[j][1]); w.y = cvt_pk_bf16(h[j][2], h[j][3]); up[64 * j] = w; }
	v_add_f32_e32 v1, v1, v94
	ds_bpermute_b32 v94, v110, v1
	v_and_b32_e32 v157, 0xffff0000, v56
	v_lshlrev_b32_e32 v56, 16, v57
	v_and_b32_e32 v57, 0xffff0000, v57
	v_lshlrev_b32_e32 v160, 16, v54
	s_waitcnt lgkmcnt(0)
	v_add_f32_e32 v1, v1, v94
	v_fmamk_f32 v1, v1, 0x3a000000, v104
	v_rsq_f32_e32 v1, v1
	v_mov_b32_e32 v94, v97
	v_and_b32_e32 v161, 0xffff0000, v54
	v_lshlrev_b32_e32 v54, 16, v55
	v_mul_f32_e32 v96, 0.5, v1
	v_pk_fma_f32 v[102:103], v[52:53], v[96:97], v[76:77] op_sel_hi:[1,0,1]
	v_mov_b32_e32 v52, v90
	v_mov_b32_e32 v53, v84
	v_pk_mul_f32 v[52:53], v[172:173], v[52:53]
	v_pk_fma_f32 v[88:89], v[86:87], v[96:97], v[78:79] op_sel_hi:[1,0,1]
	v_mov_b32_e32 v84, v91
	v_pk_fma_f32 v[86:87], v[52:53], v[96:97], v[74:75] op_sel_hi:[1,0,1]
	v_pk_mul_f32 v[76:77], v[174:175], v[84:85]
	v_mul_f32_e32 v1, v103, v103
	v_pk_mul_f32 v[52:53], v[176:177], v[92:93]
	v_pk_fma_f32 v[84:85], v[76:77], v[96:97], v[64:65] op_sel_hi:[1,0,1]
	v_pk_fma_f32 v[78:79], v[52:53], v[96:97], v[150:151] op_sel_hi:[1,0,1]
	v_pk_mul_f32 v[52:53], v[94:95], v[180:181]
	v_pk_mul_f32 v[64:65], v[178:179], v[82:83]
	v_pk_fma_f32 v[76:77], v[52:53], v[96:97], v[152:153] op_sel_hi:[1,0,1]
	v_mov_b32_e32 v52, v98
	v_mov_b32_e32 v53, v72
	v_pk_fma_f32 v[74:75], v[64:65], v[96:97], v[62:63] op_sel_hi:[1,0,1]
	v_pk_mul_f32 v[62:63], v[80:81], v[182:183]
	v_pk_mul_f32 v[52:53], v[184:185], v[52:53]
	v_mov_b32_e32 v72, v99
	v_pk_fma_f32 v[62:63], v[62:63], v[96:97], v[60:61] op_sel_hi:[1,0,1]
	v_pk_mul_f32 v[60:61], v[186:187], v[72:73]
	v_pk_fma_f32 v[68:69], v[52:53], v[96:97], v[154:155] op_sel_hi:[1,0,1]
	v_mov_b32_e32 v53, v70
	v_mov_b32_e32 v70, v101
	v_pk_fma_f32 v[60:61], v[60:61], v[96:97], v[58:59] op_sel_hi:[1,0,1]
	v_pk_mul_f32 v[58:59], v[190:191], v[70:71]
	v_mul_f32_e32 v70, v89, v89
	v_fmac_f32_e32 v1, v102, v102
	v_fmac_f32_e32 v70, v88, v88
	v_add_f32_e32 v1, v1, v70
	v_mul_f32_e32 v70, v87, v87
	v_mul_f32_e32 v71, v85, v85
	v_fmac_f32_e32 v70, v86, v86
	v_fmac_f32_e32 v71, v84, v84
	v_add_f32_e32 v70, v70, v71
	v_add_f32_e32 v1, v1, v70
	v_mul_f32_e32 v70, v79, v79
	v_mul_f32_e32 v71, v75, v75
	v_fmac_f32_e32 v70, v78, v78
	v_fmac_f32_e32 v71, v74, v74
	v_add_f32_e32 v70, v70, v71
	v_add_f32_e32 v1, v70, v1
	v_mul_f32_e32 v70, v77, v77
	v_mul_f32_e32 v71, v63, v63
	v_fmac_f32_e32 v70, v76, v76
	v_fmac_f32_e32 v71, v62, v62
	v_add_f32_e32 v70, v70, v71
	v_mov_b32_e32 v52, v100
	v_add_f32_e32 v1, v70, v1
	v_mul_f32_e32 v70, v69, v69
	v_mul_f32_e32 v71, v61, v61
	v_pk_mul_f32 v[52:53], v[188:189], v[52:53]
	v_fmac_f32_e32 v70, v68, v68
	v_fmac_f32_e32 v71, v60, v60
	v_pk_fma_f32 v[58:59], v[58:59], v[96:97], v[56:57] op_sel_hi:[1,0,1]
	v_pk_fma_f32 v[64:65], v[52:53], v[96:97], v[156:157] op_sel_hi:[1,0,1]
	v_add_f32_e32 v70, v70, v71
	v_add_f32_e32 v1, v70, v1
	v_mul_f32_e32 v70, v65, v65
	v_mul_f32_e32 v71, v59, v59
	v_and_b32_e32 v55, 0xffff0000, v55
	v_pk_mul_f32 v[56:57], v[192:193], v[140:141]
	v_pk_mul_f32 v[52:53], v[194:195], v[142:143]
	v_fmac_f32_e32 v70, v64, v64
	v_fmac_f32_e32 v71, v58, v58
	v_pk_fma_f32 v[52:53], v[96:97], v[52:53], v[54:55] op_sel_hi:[0,1,1]
	v_pk_fma_f32 v[56:57], v[96:97], v[56:57], v[160:161] op_sel_hi:[0,1,1]
	v_add_f32_e32 v70, v70, v71
	v_mov_b32_e32 v146, v145
	v_add_f32_e32 v1, v70, v1
	v_mul_f32_e32 v70, v57, v57
	v_mul_f32_e32 v71, v53, v53
	v_pk_mul_f32 v[66:67], v[146:147], v[196:197]
	v_pk_mul_f32 v[54:55], v[148:149], v[198:199]
	v_fmac_f32_e32 v70, v56, v56
	v_fmac_f32_e32 v71, v52, v52
	v_pk_fma_f32 v[54:55], v[96:97], v[54:55], v[164:165] op_sel_hi:[0,1,1]
	v_pk_fma_f32 v[66:67], v[96:97], v[66:67], v[162:163] op_sel_hi:[0,1,1]
	v_add_f32_e32 v70, v70, v71
	v_add_f32_e32 v1, v70, v1
	v_mul_f32_e32 v70, v67, v67
	v_mul_f32_e32 v71, v55, v55
	v_fmac_f32_e32 v70, v66, v66
	v_fmac_f32_e32 v71, v54, v54
	v_add_f32_e32 v70, v70, v71
	v_add_f32_e32 v1, v70, v1
	ds_bpermute_b32 v70, v105, v1
	s_waitcnt lgkmcnt(0)
	v_add_f32_e32 v1, v1, v70
	ds_bpermute_b32 v70, v106, v1
	s_waitcnt lgkmcnt(0)
	v_add_f32_e32 v1, v1, v70
	ds_bpermute_b32 v70, v107, v1
	s_waitcnt lgkmcnt(0)
	v_add_f32_e32 v1, v1, v70
	ds_bpermute_b32 v70, v108, v1
	s_waitcnt lgkmcnt(0)
	v_add_f32_e32 v1, v1, v70
	ds_bpermute_b32 v70, v109, v1
	s_waitcnt lgkmcnt(0)
	v_add_f32_e32 v1, v1, v70
	ds_bpermute_b32 v70, v110, v1
	s_and_saveexec_b64 s[2:3], s[4:5]
	s_cbranch_execz .LBB0_342
	s_waitcnt lgkmcnt(0)
	v_add_f32_e32 v1, v1, v70
	v_fmamk_f32 v1, v1, 0x3a000000, v104
	v_rsq_f32_e32 v1, v1
	v_lshl_add_u64 v[70:71], s[16:17], 0, v[4:5]
	global_store_dword v[70:71], v1, off
	s_branch .LBB0_342

; __device__ __forceinline__ unsigned cvt_pk_bf16(float lo, float hi) { unsigned r; asm volatile("v_cvt_pk_bf16_f32 %0, %1, %2" : "=v"(r) : "v"(lo), "v"(hi)); return r; }
; __device__ __forceinline__ float bf_lo(unsigned w) { return __uint_as_float(w << 16); }
; __device__ __forceinline__ float bf_hi(unsigned w) { return __uint_as_float(w & 0xffff0000u); }
; template <int MODE>
; __device__ __forceinline__ void rowwise_phase(const float* xin, bf16_t* hb, const bf16_t* f, const float* gpost, float alpha, float* rsout, float* fout, int wg, int nwg, int row0, int rowend) {
;     ...
;     if (gw < rowend) ROW_LOAD(gw);
;     for (int row = gw; row < rowend; row += NGW) {
;         f32x4 h[8]; u32x2 fw[8];
; #pragma unroll
;         for (int j = 0; j < 8; ++j) { if (XIN) h[j] = xN[j]; else h[j] = (f32x4){bf_lo(hN[j].x), bf_hi(hN[j].x), bf_lo(hN[j].y), bf_hi(hN[j].y)}; if (HASF) fw[j] = fN[j]; }
;         const int nrow = row + NGW;
;         if (nrow < rowend) ROW_LOAD(nrow);
;     ...
;             for (int j = 0; j < 8; ++j) { const f32x4 g = ((const f32x4*)gpost)[lane + 64 * j]; h[j] += fv[j] * g * rs; }
;         }
;         if (MODE == 2) {
;             f32x4* op = (f32x4*)(fout + (size_t)row * DM) + lane;
; #pragma unroll
;             for (int j = 0; j < 8; ++j) op[64 * j] = h[j];
;         } else {
;             float s2 = 0.f;
; #pragma unroll
;             for (int j = 0; j < 8; ++j) s2 += (h[j][0] * h[j][0] + h[j][1] * h[j][1]) + (h[j][2] * h[j][2] + h[j][3] * h[j][3]);
;             s2 = wave_sum(s2);
;             if (lane == 0) rsout[row] = __frsqrt_rn(s2 * (1.0f / DM) + EPS);
;             u32x2* up = (u32x2*)(hb + (size_t)row * DM) + lane;
; #pragma unroll
;             for (int j = 0; j < 8; ++j) { u32x2 w; w.x = cvt_pk_bf16(h[j][0], h[j][1]); w.y = cvt_pk_bf16(h[j][2], h[j][3]); up[64 * j] = w; }
.LBB0_730:
	s_or_b64 exec, exec, s[2:3]
	v_mov_b32_e32 v1, v158
	s_waitcnt lgkmcnt(0)
	s_barrier
	v_readlane_b32 s2, v232, 23
	v_ashrrev_i32_e32 v0, 6, v1
	s_nop 0
	v_add_u32_e32 v0, s2, v0
	v_cmp_gt_i32_e32 vcc, s13, v0
	s_and_saveexec_b64 s[8:9], vcc
	s_cbranch_execz .LBB0_737
	v_and_b32_e32 v8, 63, v1
	v_ashrrev_i32_e32 v1, 31, v0
	v_readlane_b32 s42, v232, 16
	v_lshlrev_b64 v[2:3], 12, v[0:1]
	v_readlane_b32 s40, v232, 7
	v_readlane_b32 s43, v232, 17
	v_readlane_b32 s41, v232, 8
	v_lshlrev_b32_e32 v10, 3, v8
	v_mov_b32_e32 v11, 0
	v_lshl_add_u64 v[6:7], s[42:43], 0, v[2:3]
	v_lshl_add_u64 v[4:5], s[40:41], 0, v[2:3]
	v_lshl_add_u64 v[6:7], v[6:7], 0, v[10:11]
	v_lshl_add_u64 v[4:5], v[4:5], 0, v[10:11]
	global_load_dwordx2 v[86:87], v[6:7], off
	global_load_dwordx2 v[84:85], v[6:7], off offset:512
	global_load_dwordx2 v[82:83], v[6:7], off offset:1024
	global_load_dwordx2 v[80:81], v[6:7], off offset:1536
	global_load_dwordx2 v[72:73], v[6:7], off offset:2048
	global_load_dwordx2 v[70:71], v[6:7], off offset:2560
	global_load_dwordx2 v[68:69], v[6:7], off offset:3072
	global_load_dwordx2 v[66:67], v[6:7], off offset:3584
	global_load_dwordx2 v[74:75], v[4:5], off
	global_load_dwordx2 v[64:65], v[4:5], off offset:512
	global_load_dwordx2 v[62:63], v[4:5], off offset:1024
	global_load_dwordx2 v[60:61], v[4:5], off offset:1536
	global_load_dwordx2 v[58:59], v[4:5], off offset:2048
	global_load_dwordx2 v[56:57], v[4:5], off offset:2560
	global_load_dwordx2 v[54:55], v[4:5], off offset:3072
	global_load_dwordx2 v[52:53], v[4:5], off offset:3584
	v_mbcnt_hi_u32_b32 v14, -1, v159
	v_mov_b64_e32 v[4:5], 0xbb40000
	v_and_b32_e32 v15, 64, v14
	v_xor_b32_e32 v16, 1, v14
	v_lshl_add_u64 v[4:5], v[0:1], 2, v[4:5]
	v_add_u32_e32 v1, 64, v15
	v_xor_b32_e32 v17, 2, v14
	v_cmp_lt_i32_e32 vcc, v16, v1
	s_load_dwordx2 s[2:3], s[0:1], 0x60
	v_xor_b32_e32 v18, 4, v14
	v_cmp_eq_u32_e64 s[6:7], 0, v8
	v_lshlrev_b32_e32 v12, 4, v8
	v_lshl_add_u64 v[6:7], s[40:41], 0, v[10:11]
	v_lshl_add_u64 v[8:9], s[42:43], 0, v[10:11]
	v_or_b32_e32 v2, v2, v10
	v_cndmask_b32_e32 v10, v14, v16, vcc
	v_cmp_lt_i32_e32 vcc, v17, v1
	v_xor_b32_e32 v19, 8, v14
	v_mov_b32_e32 v13, v11
	v_cndmask_b32_e32 v11, v14, v17, vcc
	v_cmp_lt_i32_e32 vcc, v18, v1
	v_xor_b32_e32 v20, 16, v14
	v_xor_b32_e32 v21, 32, v14
	v_cndmask_b32_e32 v15, v14, v18, vcc
	v_cmp_lt_i32_e32 vcc, v19, v1
	s_mov_b64 s[10:11], 0x1000
	s_mov_b64 s[22:23], 0x1400
	v_cndmask_b32_e32 v16, v14, v19, vcc
	v_cmp_lt_i32_e32 vcc, v20, v1
	s_mov_b64 s[28:29], 0x1800
	s_mov_b64 s[36:37], 0x1c00
	v_cndmask_b32_e32 v17, v14, v20, vcc
	v_cmp_lt_i32_e32 vcc, v21, v1
	s_ashr_i32 s27, s26, 31
	v_lshlrev_b32_e32 v105, 2, v10
	v_cndmask_b32_e32 v1, v14, v21, vcc
	v_lshlrev_b32_e32 v106, 2, v11
	s_waitcnt lgkmcnt(0)
	v_lshl_add_u64 v[10:11], s[2:3], 0, v[12:13]
	s_mov_b64 s[30:31], 0
	v_mov_b32_e32 v104, 0x358637bd
	s_lshl_b64 s[34:35], s[26:27], 2
	s_lshl_b64 s[38:39], s[26:27], 12
	v_lshlrev_b32_e32 v107, 2, v15
	v_lshlrev_b32_e32 v108, 2, v16
	v_lshlrev_b32_e32 v109, 2, v17
	v_lshlrev_b32_e32 v110, 2, v1
	v_lshl_add_u64 v[12:13], v[10:11], 0, s[10:11]
	v_lshl_add_u64 v[14:15], v[10:11], 0, s[22:23]
	v_lshl_add_u64 v[16:17], v[10:11], 0, s[28:29]
	v_lshl_add_u64 v[18:19], v[10:11], 0, s[36:37]
	s_waitcnt vmcnt(15)
	v_mov_b64_e32 v[22:23], v[86:87]
	s_waitcnt vmcnt(14)
	v_mov_b64_e32 v[26:27], v[84:85]
	s_waitcnt vmcnt(13)
	v_mov_b64_e32 v[30:31], v[82:83]
	s_waitcnt vmcnt(12)
	v_mov_b64_e32 v[34:35], v[80:81]
	s_waitcnt vmcnt(11)
	v_mov_b64_e32 v[38:39], v[72:73]
	s_waitcnt vmcnt(10)
	v_mov_b64_e32 v[42:43], v[70:71]
	s_waitcnt vmcnt(9)
	v_mov_b64_e32 v[46:47], v[68:69]
	s_waitcnt vmcnt(8)
	v_mov_b64_e32 v[50:51], v[66:67]
	s_waitcnt vmcnt(7)
	v_mov_b64_e32 v[20:21], v[74:75]
	s_waitcnt vmcnt(6)
	v_mov_b64_e32 v[24:25], v[64:65]
	s_waitcnt vmcnt(5)
	v_mov_b64_e32 v[28:29], v[62:63]
	s_waitcnt vmcnt(4)
	v_mov_b64_e32 v[32:33], v[60:61]
	s_waitcnt vmcnt(3)
	v_mov_b64_e32 v[36:37], v[58:59]
	s_waitcnt vmcnt(2)
	v_mov_b64_e32 v[40:41], v[56:57]
	s_waitcnt vmcnt(1)
	v_mov_b64_e32 v[44:45], v[54:55]
	s_waitcnt vmcnt(0)
	v_mov_b64_e32 v[48:49], v[52:53]
	global_load_dwordx4 v[168:171], v[10:11], off
	global_load_dwordx4 v[172:175], v[10:11], off offset:2048
	global_load_dwordx4 v[176:179], v[10:11], off offset:1024
	global_load_dwordx4 v[180:183], v[10:11], off offset:3072
	global_load_dwordx4 v[184:187], v[12:13], off
	global_load_dwordx4 v[188:191], v[14:15], off
	global_load_dwordx4 v[192:195], v[16:17], off
	global_load_dwordx4 v[196:199], v[18:19], off
	s_waitcnt vmcnt(0)
	s_branch .LBB0_733
.LBB0_732:
	s_or_b64 exec, exec, s[2:3]
	s_waitcnt lgkmcnt(0)
	v_lshl_add_u64 v[70:71], s[16:17], 0, v[2:3]
	s_and_b64 s[2:3], exec, vcc
	v_add_co_u32_e32 v70, vcc, 0xbb50000, v70
	v_cvt_pk_bf16_f32 v72, v102, v103
	v_cvt_pk_bf16_f32 v73, v88, v89
	s_or_b64 s[30:31], s[2:3], s[30:31]
	s_nop 0
	v_addc_co_u32_e32 v71, vcc, 0, v71, vcc
	global_store_dwordx2 v[70:71], v[72:73], off
	v_cvt_pk_bf16_f32 v72, v86, v87
	v_cvt_pk_bf16_f32 v73, v84, v85
	global_store_dwordx2 v[70:71], v[72:73], off offset:512
	v_cvt_pk_bf16_f32 v72, v78, v79
	v_cvt_pk_bf16_f32 v73, v74, v75
	global_store_dwordx2 v[70:71], v[72:73], off offset:1024
	v_cvt_pk_bf16_f32 v72, v76, v77
	v_cvt_pk_bf16_f32 v73, v62, v63
	global_store_dwordx2 v[70:71], v[72:73], off offset:1536
	v_cvt_pk_bf16_f32 v62, v68, v69
	v_cvt_pk_bf16_f32 v63, v60, v61
	global_store_dwordx2 v[70:71], v[62:63], off offset:2048
	v_cvt_pk_bf16_f32 v60, v64, v65
	v_cvt_pk_bf16_f32 v61, v58, v59
	global_store_dwordx2 v[70:71], v[60:61], off offset:2560
	v_cvt_pk_bf16_f32 v56, v56, v57
	v_cvt_pk_bf16_f32 v57, v52, v53
	global_store_dwordx2 v[70:71], v[56:57], off offset:3072
	v_cvt_pk_bf16_f32 v52, v66, v67
	v_cvt_pk_bf16_f32 v53, v54, v55
	global_store_dwordx2 v[70:71], v[52:53], off offset:3584
	v_lshl_add_u64 v[4:5], v[4:5], 0, s[34:35]
	v_lshl_add_u64 v[2:3], v[2:3], 0, s[38:39]
	s_waitcnt vmcnt(9)
	v_mov_b64_e32 v[86:87], v[22:23]
	v_mov_b64_e32 v[84:85], v[26:27]
	v_mov_b64_e32 v[82:83], v[30:31]
	v_mov_b64_e32 v[80:81], v[34:35]
	v_mov_b64_e32 v[72:73], v[38:39]
	v_mov_b64_e32 v[70:71], v[42:43]
	v_mov_b64_e32 v[68:69], v[46:47]
	v_mov_b64_e32 v[66:67], v[50:51]
	v_mov_b64_e32 v[74:75], v[20:21]
	v_mov_b64_e32 v[64:65], v[24:25]
	v_mov_b64_e32 v[62:63], v[28:29]
	v_mov_b64_e32 v[60:61], v[32:33]
	v_mov_b64_e32 v[58:59], v[36:37]
	v_mov_b64_e32 v[56:57], v[40:41]
	v_mov_b64_e32 v[54:55], v[44:45]
	v_mov_b64_e32 v[52:53], v[48:49]
	s_andn2_b64 exec, exec, s[30:31]
	s_cbranch_execz .LBB0_737

; __device__ __forceinline__ float bf_lo(unsigned w) { return __uint_as_float(w << 16); }
; __device__ __forceinline__ float bf_hi(unsigned w) { return __uint_as_float(w & 0xffff0000u); }
; template <int MODE>
; __device__ __forceinline__ void rowwise_phase(const float* xin, bf16_t* hb, const bf16_t* f, const float* gpost, float alpha, float* rsout, float* fout, int wg, int nwg, int row0, int rowend) {
;     ...
;         if (HASF) {
;             f32x4 fv[8]; float ss = 0.f;
; #pragma unroll
;             for (int j = 0; j < 8; ++j) { const u32x2 w = fw[j]; fv[j] = (f32x4){bf_lo(w.x), bf_hi(w.x), bf_lo(w.y), bf_hi(w.y)};
;                 ss += (fv[j][0] * fv[j][0] + fv[j][1] * fv[j][1]) + (fv[j][2] * fv[j][2] + fv[j][3] * fv[j][3]); }
;             ss = wave_sum(ss);
;             const float rs = alpha * __frsqrt_rn(ss * (1.0f / DM) + EPS);
; #pragma unroll
;             for (int j = 0; j < 8; ++j) { const f32x4 g = ((const f32x4*)gpost)[lane + 64 * j]; h[j] += fv[j] * g * rs; }
.LBB0_735:
	s_or_b64 exec, exec, s[40:41]
	v_lshlrev_b32_e32 v88, 16, v86
	v_and_b32_e32 v89, 0xffff0000, v86
	v_lshlrev_b32_e32 v86, 16, v87
	v_and_b32_e32 v87, 0xffff0000, v87
	v_mul_f32_e32 v90, v87, v87
	v_pk_fma_f32 v[98:99], v[86:87], v[86:87], v[90:91] op_sel_hi:[1,1,0]
	v_lshlrev_b32_e32 v91, 16, v85
	v_lshlrev_b32_e32 v90, 16, v84
	v_and_b32_e32 v85, 0xffff0000, v85
	v_and_b32_e32 v84, 0xffff0000, v84
	v_and_b32_e32 v95, 0xffff0000, v80
	v_mul_f32_e32 v94, v89, v89
	v_pk_mul_f32 v[92:93], v[84:85], v[84:85]
	v_lshlrev_b32_e32 v97, 16, v80
	v_pk_fma_f32 v[102:103], v[88:89], v[88:89], v[94:95] op_sel_hi:[1,1,0]
	v_pk_fma_f32 v[100:101], v[90:91], v[90:91], v[92:93]
	v_mov_b32_e32 v96, v102
	v_mov_b32_e32 v112, v98
	v_mov_b32_e32 v113, v97
	v_and_b32_e32 v93, 0xffff0000, v82
	v_mul_f32_e32 v1, v95, v95
	v_pk_add_f32 v[98:99], v[102:103], v[98:99]
	v_pk_mul_f32 v[102:103], v[96:97], v[112:113]
	v_pk_add_f32 v[100:101], v[100:101], v[100:101] op_sel:[0,1] op_sel_hi:[1,0]
	v_lshlrev_b32_e32 v92, 16, v82
	v_lshlrev_b32_e32 v82, 16, v83
	v_and_b32_e32 v83, 0xffff0000, v83
	v_mov_b32_e32 v99, v103
	v_mov_b32_e32 v101, v1
	v_mul_f32_e32 v94, v93, v93
	v_lshlrev_b32_e32 v80, 16, v81
	v_and_b32_e32 v81, 0xffff0000, v81
	v_pk_add_f32 v[98:99], v[98:99], v[100:101]
	v_pk_fma_f32 v[100:101], v[92:93], v[92:93], v[94:95] op_sel_hi:[1,1,0]
	v_mul_f32_e32 v94, v83, v83
	v_mul_f32_e32 v111, v80, v80
	v_mul_f32_e32 v114, v81, v81
	v_pk_fma_f32 v[102:103], v[82:83], v[82:83], v[94:95] op_sel_hi:[1,1,0]
	v_mov_b32_e32 v101, v111
	v_mov_b32_e32 v103, v114
	v_pk_add_f32 v[100:101], v[100:101], v[102:103]
	v_pk_add_f32 v[102:103], v[98:99], v[100:101]
	v_lshlrev_b32_e32 v99, 16, v73
	v_lshlrev_b32_e32 v98, 16, v72
	v_and_b32_e32 v73, 0xffff0000, v73
	v_and_b32_e32 v72, 0xffff0000, v72
	v_pk_mul_f32 v[100:101], v[72:73], v[72:73]
	v_lshlrev_b32_e32 v145, 16, v66
	v_pk_fma_f32 v[100:101], v[98:99], v[98:99], v[100:101]
	v_pk_add_f32 v[128:129], v[100:101], v[100:101] op_sel:[0,1] op_sel_hi:[1,0]
	v_lshlrev_b32_e32 v101, 16, v71
	v_lshlrev_b32_e32 v100, 16, v70
	v_and_b32_e32 v71, 0xffff0000, v71
	v_and_b32_e32 v70, 0xffff0000, v70
	v_pk_mul_f32 v[116:117], v[70:71], v[70:71]
	v_pk_add_f32 v[102:103], v[102:103], v[102:103] op_sel:[0,1] op_sel_hi:[1,0]
	v_pk_fma_f32 v[130:131], v[100:101], v[100:101], v[116:117]
	v_lshlrev_b32_e32 v140, 16, v68
	v_and_b32_e32 v141, 0xffff0000, v68
	v_lshlrev_b32_e32 v142, 16, v69
	v_and_b32_e32 v143, 0xffff0000, v69
	v_and_b32_e32 v147, 0xffff0000, v66
	v_lshlrev_b32_e32 v148, 16, v67
	v_and_b32_e32 v149, 0xffff0000, v67
	v_mov_b32_e32 v144, v102
	v_mov_b32_e32 v132, v128
	v_mov_b32_e32 v133, v145
	v_pk_add_f32 v[102:103], v[102:103], v[128:129]
	v_pk_mul_f32 v[128:129], v[144:145], v[132:133]
	v_mul_f32_e32 v1, v147, v147
	v_mov_b32_e32 v103, v129
	v_pk_add_f32 v[128:129], v[130:131], v[130:131] op_sel:[0,1] op_sel_hi:[1,0]
	v_mul_f32_e32 v94, v141, v141
	v_mov_b32_e32 v129, v1
	v_pk_add_f32 v[102:103], v[102:103], v[128:129]
	v_pk_fma_f32 v[136:137], v[140:141], v[140:141], v[94:95] op_sel_hi:[1,1,0]
	v_mul_f32_e32 v94, v143, v143
	v_mul_f32_e32 v96, v148, v148
	v_mul_f32_e32 v111, v149, v149
	v_pk_fma_f32 v[138:139], v[142:143], v[142:143], v[94:95] op_sel_hi:[1,1,0]
	v_mov_b32_e32 v137, v96
	v_mov_b32_e32 v139, v111
	v_pk_add_f32 v[136:137], v[136:137], v[138:139]
	v_lshlrev_b32_e32 v76, 16, v74
	v_pk_add_f32 v[102:103], v[102:103], v[136:137]
	v_add_f32_e32 v1, v102, v103
	ds_bpermute_b32 v94, v105, v1
	v_and_b32_e32 v77, 0xffff0000, v74
	v_lshlrev_b32_e32 v162, 16, v52
	v_and_b32_e32 v163, 0xffff0000, v52
	v_lshlrev_b32_e32 v164, 16, v53
	s_waitcnt lgkmcnt(0)
	v_add_f32_e32 v1, v1, v94
	ds_bpermute_b32 v94, v106, v1
	v_and_b32_e32 v165, 0xffff0000, v53
	v_lshlrev_b32_e32 v78, 16, v75
	v_and_b32_e32 v79, 0xffff0000, v75
	v_lshlrev_b32_e32 v74, 16, v64
	s_waitcnt lgkmcnt(0)
	v_add_f32_e32 v1, v1, v94
	ds_bpermute_b32 v94, v107, v1
	v_and_b32_e32 v75, 0xffff0000, v64
	v_lshlrev_b32_e32 v150, 16, v62
	v_and_b32_e32 v151, 0xffff0000, v62
	v_lshlrev_b32_e32 v64, 16, v65
	s_waitcnt lgkmcnt(0)
	v_add_f32_e32 v1, v1, v94
	ds_bpermute_b32 v94, v108, v1
	v_and_b32_e32 v65, 0xffff0000, v65
	v_lshlrev_b32_e32 v152, 16, v60
	v_and_b32_e32 v153, 0xffff0000, v60
	v_lshlrev_b32_e32 v62, 16, v63
	s_waitcnt lgkmcnt(0)
	v_add_f32_e32 v1, v1, v94
	ds_bpermute_b32 v94, v109, v1
	v_and_b32_e32 v63, 0xffff0000, v63
	v_lshlrev_b32_e32 v60, 16, v61
	v_pk_mul_f32 v[52:53], v[168:169], v[88:89]
	v_pk_mul_f32 v[86:87], v[170:171], v[86:87]
	s_waitcnt lgkmcnt(0)
; __device__ __forceinline__ unsigned cvt_pk_bf16(float lo, float hi) { unsigned r; asm volatile("v_cvt_pk_bf16_f32 %0, %1, %2" : "=v"(r) : "v"(lo), "v"(hi)); return r; }
; template <int MODE>
; __device__ __forceinline__ void rowwise_phase(const float* xin, bf16_t* hb, const bf16_t* f, const float* gpost, float alpha, float* rsout, float* fout, int wg, int nwg, int row0, int rowend) {
;     ...
;             ss = wave_sum(ss);
;             const float rs = alpha * __frsqrt_rn(ss * (1.0f / DM) + EPS);
; #pragma unroll
;             for (int j = 0; j < 8; ++j) { const f32x4 g = ((const f32x4*)gpost)[lane + 64 * j]; h[j] += fv[j] * g * rs; }
;         }
;         if (MODE == 2) {
;             f32x4* op = (f32x4*)(fout + (size_t)row * DM) + lane;
; #pragma unroll
;             for (int j = 0; j < 8; ++j) op[64 * j] = h[j];
;         } else {
;             float s2 = 0.f;
; #pragma unroll
;             for (int j = 0; j < 8; ++j) s2 += (h[j][0] * h[j][0] + h[j][1] * h[j][1]) + (h[j][2] * h[j][2] + h[j][3] * h[j][3]);
;             s2 = wave_sum(s2);
;             if (lane == 0) rsout[row] = __frsqrt_rn(s2 * (1.0f / DM) + EPS);
;             u32x2* up = (u32x2*)(hb + (size_t)row * DM) + lane;
; #pragma unroll
;             for (int j = 0; j < 8; ++j) { u32x2 w; w.x = cvt_pk_bf16(h[j][0], h[j][1]); w.y = cvt_pk_bf16(h[j][2], h[j][3]); up[64 * j] = w; }
	v_add_f32_e32 v1, v1, v94
	ds_bpermute_b32 v94, v110, v1
	v_and_b32_e32 v61, 0xffff0000, v61
	v_lshlrev_b32_e32 v154, 16, v58
	v_and_b32_e32 v155, 0xffff0000, v58
	v_lshlrev_b32_e32 v58, 16, v59
	s_waitcnt lgkmcnt(0)
	v_add_f32_e32 v1, v1, v94
	v_fmamk_f32 v1, v1, 0x3a000000, v104
	v_rsq_f32_e32 v96, v1
	v_mov_b32_e32 v94, v97
	v_and_b32_e32 v59, 0xffff0000, v59
	v_lshlrev_b32_e32 v156, 16, v56
	v_pk_fma_f32 v[102:103], v[52:53], v[96:97], v[76:77] op_sel_hi:[1,0,1]
	v_mov_b32_e32 v52, v90
	v_mov_b32_e32 v53, v84
	v_pk_fma_f32 v[88:89], v[86:87], v[96:97], v[78:79] op_sel_hi:[1,0,1]
	v_pk_mul_f32 v[52:53], v[176:177], v[52:53]
	v_mov_b32_e32 v84, v91
	v_pk_fma_f32 v[86:87], v[52:53], v[96:97], v[74:75] op_sel_hi:[1,0,1]
	v_pk_mul_f32 v[52:53], v[172:173], v[92:93]
	v_pk_mul_f32 v[76:77], v[178:179], v[84:85]
	v_pk_fma_f32 v[78:79], v[52:53], v[96:97], v[150:151] op_sel_hi:[1,0,1]
	v_pk_fma_f32 v[84:85], v[76:77], v[96:97], v[64:65] op_sel_hi:[1,0,1]
	v_pk_mul_f32 v[64:65], v[174:175], v[82:83]
	v_pk_mul_f32 v[52:53], v[94:95], v[180:181]
	v_pk_fma_f32 v[74:75], v[64:65], v[96:97], v[62:63] op_sel_hi:[1,0,1]
	v_pk_fma_f32 v[76:77], v[52:53], v[96:97], v[152:153] op_sel_hi:[1,0,1]
	v_mov_b32_e32 v52, v98
	v_mov_b32_e32 v53, v72
	v_pk_mul_f32 v[62:63], v[80:81], v[182:183]
	v_mov_b32_e32 v72, v99
	v_pk_mul_f32 v[52:53], v[184:185], v[52:53]
	v_pk_fma_f32 v[62:63], v[62:63], v[96:97], v[60:61] op_sel_hi:[1,0,1]
	v_pk_mul_f32 v[60:61], v[186:187], v[72:73]
	v_pk_fma_f32 v[68:69], v[52:53], v[96:97], v[154:155] op_sel_hi:[1,0,1]
	v_mov_b32_e32 v53, v70
	v_mov_b32_e32 v70, v101
	v_pk_fma_f32 v[60:61], v[60:61], v[96:97], v[58:59] op_sel_hi:[1,0,1]
	v_pk_mul_f32 v[58:59], v[190:191], v[70:71]
	v_mul_f32_e32 v1, v103, v103
	v_mul_f32_e32 v70, v89, v89
	v_fmac_f32_e32 v1, v102, v102
	v_fmac_f32_e32 v70, v88, v88
	v_add_f32_e32 v1, v1, v70
	v_mul_f32_e32 v70, v87, v87
	v_mul_f32_e32 v71, v85, v85
	v_fmac_f32_e32 v70, v86, v86
	v_fmac_f32_e32 v71, v84, v84
	v_add_f32_e32 v70, v70, v71
	v_add_f32_e32 v1, v1, v70
	v_mul_f32_e32 v70, v79, v79
	v_mul_f32_e32 v71, v75, v75
	v_fmac_f32_e32 v70, v78, v78
	v_fmac_f32_e32 v71, v74, v74
	v_add_f32_e32 v70, v70, v71
	v_add_f32_e32 v1, v70, v1
	v_mul_f32_e32 v70, v77, v77
	v_mul_f32_e32 v71, v63, v63
	v_fmac_f32_e32 v70, v76, v76
	v_fmac_f32_e32 v71, v62, v62
	v_add_f32_e32 v70, v70, v71
	v_mov_b32_e32 v52, v100
	v_add_f32_e32 v1, v70, v1
	v_mul_f32_e32 v70, v69, v69
	v_mul_f32_e32 v71, v61, v61
	v_and_b32_e32 v157, 0xffff0000, v56
	v_lshlrev_b32_e32 v56, 16, v57
	v_and_b32_e32 v57, 0xffff0000, v57
	v_pk_mul_f32 v[52:53], v[188:189], v[52:53]
	v_fmac_f32_e32 v70, v68, v68
	v_fmac_f32_e32 v71, v60, v60
	v_pk_fma_f32 v[58:59], v[96:97], v[58:59], v[56:57] op_sel_hi:[0,1,1]
	v_pk_fma_f32 v[64:65], v[96:97], v[52:53], v[156:157] op_sel_hi:[0,1,1]
	v_add_f32_e32 v70, v70, v71
	v_add_f32_e32 v1, v70, v1
	v_mul_f32_e32 v70, v65, v65
	v_mul_f32_e32 v71, v59, v59
	v_lshlrev_b32_e32 v160, 16, v54
	v_and_b32_e32 v161, 0xffff0000, v54
	v_lshlrev_b32_e32 v54, 16, v55
	v_and_b32_e32 v55, 0xffff0000, v55
	v_pk_mul_f32 v[56:57], v[192:193], v[140:141]
	v_pk_mul_f32 v[52:53], v[194:195], v[142:143]
	v_fmac_f32_e32 v70, v64, v64
	v_fmac_f32_e32 v71, v58, v58
	v_pk_fma_f32 v[52:53], v[96:97], v[52:53], v[54:55] op_sel_hi:[0,1,1]
	v_pk_fma_f32 v[56:57], v[96:97], v[56:57], v[160:161] op_sel_hi:[0,1,1]
	v_add_f32_e32 v70, v70, v71
	v_mov_b32_e32 v146, v145
	v_add_f32_e32 v1, v70, v1
	v_mul_f32_e32 v70, v57, v57
	v_mul_f32_e32 v71, v53, v53
	v_pk_mul_f32 v[66:67], v[146:147], v[196:197]
	v_pk_mul_f32 v[54:55], v[148:149], v[198:199]
	v_fmac_f32_e32 v70, v56, v56
	v_fmac_f32_e32 v71, v52, v52
	v_pk_fma_f32 v[54:55], v[96:97], v[54:55], v[164:165] op_sel_hi:[0,1,1]
	v_pk_fma_f32 v[66:67], v[96:97], v[66:67], v[162:163] op_sel_hi:[0,1,1]
	v_add_f32_e32 v70, v70, v71
	v_add_f32_e32 v1, v70, v1
	v_mul_f32_e32 v70, v67, v67
	v_mul_f32_e32 v71, v55, v55
	v_fmac_f32_e32 v70, v66, v66
	v_fmac_f32_e32 v71, v54, v54
	v_add_f32_e32 v70, v70, v71
	v_add_f32_e32 v1, v70, v1
	ds_bpermute_b32 v70, v105, v1
	s_waitcnt lgkmcnt(0)
	v_add_f32_e32 v1, v1, v70
	ds_bpermute_b32 v70, v106, v1
	s_waitcnt lgkmcnt(0)
	v_add_f32_e32 v1, v1, v70
	ds_bpermute_b32 v70, v107, v1
	s_waitcnt lgkmcnt(0)
	v_add_f32_e32 v1, v1, v70
	ds_bpermute_b32 v70, v108, v1
	s_waitcnt lgkmcnt(0)
	v_add_f32_e32 v1, v1, v70
	ds_bpermute_b32 v70, v109, v1
	s_waitcnt lgkmcnt(0)
	v_add_f32_e32 v1, v1, v70
	ds_bpermute_b32 v70, v110, v1
	s_and_saveexec_b64 s[2:3], s[6:7]
	s_cbranch_execz .LBB0_732
	s_waitcnt lgkmcnt(0)
	v_add_f32_e32 v1, v1, v70
	v_fmamk_f32 v1, v1, 0x3a000000, v104
	v_rsq_f32_e32 v1, v1
	v_lshl_add_u64 v[70:71], s[16:17], 0, v[4:5]
	global_store_dword v[70:71], v1, off
	s_branch .LBB0_732

; __device__ __forceinline__ unsigned cvt_pk_bf16(float lo, float hi) { unsigned r; asm volatile("v_cvt_pk_bf16_f32 %0, %1, %2" : "=v"(r) : "v"(lo), "v"(hi)); return r; }
; __device__ __forceinline__ float bf_lo(unsigned w) { return __uint_as_float(w << 16); }
; __device__ __forceinline__ float bf_hi(unsigned w) { return __uint_as_float(w & 0xffff0000u); }
; template <int MODE>
; __device__ __forceinline__ void rowwise_phase(const float* xin, bf16_t* hb, const bf16_t* f, const float* gpost, float alpha, float* rsout, float* fout, int wg, int nwg, int row0, int rowend) {
;     ...
;     if (gw < rowend) ROW_LOAD(gw);
;     for (int row = gw; row < rowend; row += NGW) {
;         f32x4 h[8]; u32x2 fw[8];
; #pragma unroll
;         for (int j = 0; j < 8; ++j) { if (XIN) h[j] = xN[j]; else h[j] = (f32x4){bf_lo(hN[j].x), bf_hi(hN[j].x), bf_lo(hN[j].y), bf_hi(hN[j].y)}; if (HASF) fw[j] = fN[j]; }
;         const int nrow = row + NGW;
;         if (nrow < rowend) ROW_LOAD(nrow);
;     ...
;             for (int j = 0; j < 8; ++j) { const f32x4 g = ((const f32x4*)gpost)[lane + 64 * j]; h[j] += fv[j] * g * rs; }
;         }
;         if (MODE == 2) {
;             f32x4* op = (f32x4*)(fout + (size_t)row * DM) + lane;
; #pragma unroll
;             for (int j = 0; j < 8; ++j) op[64 * j] = h[j];
;         } else {
;             float s2 = 0.f;
; #pragma unroll
;             for (int j = 0; j < 8; ++j) s2 += (h[j][0] * h[j][0] + h[j][1] * h[j][1]) + (h[j][2] * h[j][2] + h[j][3] * h[j][3]);
;             s2 = wave_sum(s2);
;             if (lane == 0) rsout[row] = __frsqrt_rn(s2 * (1.0f / DM) + EPS);
;             u32x2* up = (u32x2*)(hb + (size_t)row * DM) + lane;
; #pragma unroll
;             for (int j = 0; j < 8; ++j) { u32x2 w; w.x = cvt_pk_bf16(h[j][0], h[j][1]); w.y = cvt_pk_bf16(h[j][2], h[j][3]); up[64 * j] = w; }
.LBB0_921:
	s_or_b64 exec, exec, s[2:3]
	v_mov_b32_e32 v1, v158
	s_waitcnt lgkmcnt(0)
	s_barrier
	v_readlane_b32 s2, v232, 23
	v_ashrrev_i32_e32 v0, 6, v1
	s_nop 0
	v_add_u32_e32 v0, s2, v0
	v_cmp_gt_i32_e32 vcc, s13, v0
	s_and_saveexec_b64 s[8:9], vcc
	s_cbranch_execz .LBB0_928
	v_and_b32_e32 v8, 63, v1
	v_ashrrev_i32_e32 v1, 31, v0
	v_readlane_b32 s42, v232, 16
	v_lshlrev_b64 v[2:3], 12, v[0:1]
	v_readlane_b32 s40, v232, 7
	v_readlane_b32 s43, v232, 17
	v_readlane_b32 s41, v232, 8
	v_lshlrev_b32_e32 v10, 3, v8
	v_mov_b32_e32 v11, 0
	v_lshl_add_u64 v[6:7], s[42:43], 0, v[2:3]
	v_lshl_add_u64 v[4:5], s[40:41], 0, v[2:3]
	v_lshl_add_u64 v[6:7], v[6:7], 0, v[10:11]
	v_lshl_add_u64 v[4:5], v[4:5], 0, v[10:11]
	global_load_dwordx2 v[86:87], v[6:7], off
	global_load_dwordx2 v[84:85], v[6:7], off offset:512
	global_load_dwordx2 v[82:83], v[6:7], off offset:1024
	global_load_dwordx2 v[80:81], v[6:7], off offset:1536
	global_load_dwordx2 v[72:73], v[6:7], off offset:2048
	global_load_dwordx2 v[70:71], v[6:7], off offset:2560
	global_load_dwordx2 v[68:69], v[6:7], off offset:3072
	global_load_dwordx2 v[66:67], v[6:7], off offset:3584
	global_load_dwordx2 v[74:75], v[4:5], off
	global_load_dwordx2 v[64:65], v[4:5], off offset:512
	global_load_dwordx2 v[62:63], v[4:5], off offset:1024
	global_load_dwordx2 v[60:61], v[4:5], off offset:1536
	global_load_dwordx2 v[58:59], v[4:5], off offset:2048
	global_load_dwordx2 v[56:57], v[4:5], off offset:2560
	global_load_dwordx2 v[54:55], v[4:5], off offset:3072
	global_load_dwordx2 v[52:53], v[4:5], off offset:3584
	v_mbcnt_hi_u32_b32 v14, -1, v159
	v_mov_b64_e32 v[4:5], 0xbb40000
	v_and_b32_e32 v15, 64, v14
	v_xor_b32_e32 v16, 1, v14
	v_lshl_add_u64 v[4:5], v[0:1], 2, v[4:5]
	v_add_u32_e32 v1, 64, v15
	v_xor_b32_e32 v17, 2, v14
	v_cmp_lt_i32_e32 vcc, v16, v1
	s_load_dwordx2 s[2:3], s[0:1], 0x88
	v_xor_b32_e32 v18, 4, v14
	v_cmp_eq_u32_e64 s[6:7], 0, v8
	v_lshlrev_b32_e32 v12, 4, v8
	v_lshl_add_u64 v[6:7], s[40:41], 0, v[10:11]
	v_lshl_add_u64 v[8:9], s[42:43], 0, v[10:11]
	v_or_b32_e32 v2, v2, v10
	v_cndmask_b32_e32 v10, v14, v16, vcc
	v_cmp_lt_i32_e32 vcc, v17, v1
	v_xor_b32_e32 v19, 8, v14
	v_mov_b32_e32 v13, v11
	v_cndmask_b32_e32 v11, v14, v17, vcc
	v_cmp_lt_i32_e32 vcc, v18, v1
	v_xor_b32_e32 v20, 16, v14
	v_xor_b32_e32 v21, 32, v14
	v_cndmask_b32_e32 v15, v14, v18, vcc
	v_cmp_lt_i32_e32 vcc, v19, v1
	s_mov_b64 s[10:11], 0x1000
	s_mov_b64 s[22:23], 0x1400
	v_cndmask_b32_e32 v16, v14, v19, vcc
	v_cmp_lt_i32_e32 vcc, v20, v1
	s_mov_b64 s[28:29], 0x1800
	s_mov_b64 s[38:39], 0x1c00
	v_cndmask_b32_e32 v17, v14, v20, vcc
	v_cmp_lt_i32_e32 vcc, v21, v1
	s_ashr_i32 s27, s26, 31
	v_lshlrev_b32_e32 v105, 2, v10
	v_cndmask_b32_e32 v1, v14, v21, vcc
	v_lshlrev_b32_e32 v106, 2, v11
	s_waitcnt lgkmcnt(0)
	v_lshl_add_u64 v[10:11], s[2:3], 0, v[12:13]
	s_mov_b64 s[30:31], 0
	v_mov_b32_e32 v104, 0x358637bd
	s_lshl_b64 s[34:35], s[26:27], 2
	s_lshl_b64 s[36:37], s[26:27], 12
	v_lshlrev_b32_e32 v107, 2, v15
	v_lshlrev_b32_e32 v108, 2, v16
	v_lshlrev_b32_e32 v109, 2, v17
	v_lshlrev_b32_e32 v110, 2, v1
	v_lshl_add_u64 v[12:13], v[10:11], 0, s[10:11]
	v_lshl_add_u64 v[14:15], v[10:11], 0, s[22:23]
	v_lshl_add_u64 v[16:17], v[10:11], 0, s[28:29]
	v_lshl_add_u64 v[18:19], v[10:11], 0, s[38:39]
	s_waitcnt vmcnt(15)
	v_mov_b64_e32 v[22:23], v[86:87]
	s_waitcnt vmcnt(14)
	v_mov_b64_e32 v[26:27], v[84:85]
	s_waitcnt vmcnt(13)
	v_mov_b64_e32 v[30:31], v[82:83]
	s_waitcnt vmcnt(12)
	v_mov_b64_e32 v[34:35], v[80:81]
	s_waitcnt vmcnt(11)
	v_mov_b64_e32 v[38:39], v[72:73]
	s_waitcnt vmcnt(10)
	v_mov_b64_e32 v[42:43], v[70:71]
	s_waitcnt vmcnt(9)
	v_mov_b64_e32 v[46:47], v[68:69]
	s_waitcnt vmcnt(8)
	v_mov_b64_e32 v[50:51], v[66:67]
	s_waitcnt vmcnt(7)
	v_mov_b64_e32 v[20:21], v[74:75]
	s_waitcnt vmcnt(6)
	v_mov_b64_e32 v[24:25], v[64:65]
	s_waitcnt vmcnt(5)
	v_mov_b64_e32 v[28:29], v[62:63]
	s_waitcnt vmcnt(4)
	v_mov_b64_e32 v[32:33], v[60:61]
	s_waitcnt vmcnt(3)
	v_mov_b64_e32 v[36:37], v[58:59]
	s_waitcnt vmcnt(2)
	v_mov_b64_e32 v[40:41], v[56:57]
	s_waitcnt vmcnt(1)
	v_mov_b64_e32 v[44:45], v[54:55]
	s_waitcnt vmcnt(0)
	v_mov_b64_e32 v[48:49], v[52:53]
	global_load_dwordx4 v[168:171], v[10:11], off
	global_load_dwordx4 v[172:175], v[10:11], off offset:1024
	global_load_dwordx4 v[176:179], v[10:11], off offset:2048
	global_load_dwordx4 v[180:183], v[10:11], off offset:3072
	global_load_dwordx4 v[184:187], v[12:13], off
	global_load_dwordx4 v[188:191], v[14:15], off
	global_load_dwordx4 v[192:195], v[16:17], off
	global_load_dwordx4 v[196:199], v[18:19], off
	s_waitcnt vmcnt(0)
	s_branch .LBB0_924
.LBB0_923:
	s_or_b64 exec, exec, s[2:3]
	s_waitcnt lgkmcnt(0)
	v_lshl_add_u64 v[70:71], s[16:17], 0, v[2:3]
	s_and_b64 s[2:3], exec, vcc
	v_add_co_u32_e32 v70, vcc, 0xbb50000, v70
	v_cvt_pk_bf16_f32 v72, v102, v103
	v_cvt_pk_bf16_f32 v73, v88, v89
	s_or_b64 s[30:31], s[2:3], s[30:31]
	s_nop 0
	v_addc_co_u32_e32 v71, vcc, 0, v71, vcc
	global_store_dwordx2 v[70:71], v[72:73], off
	v_cvt_pk_bf16_f32 v72, v86, v87
	v_cvt_pk_bf16_f32 v73, v84, v85
	global_store_dwordx2 v[70:71], v[72:73], off offset:512
	v_cvt_pk_bf16_f32 v72, v78, v79
	v_cvt_pk_bf16_f32 v73, v74, v75
	global_store_dwordx2 v[70:71], v[72:73], off offset:1024
	v_cvt_pk_bf16_f32 v72, v76, v77
	v_cvt_pk_bf16_f32 v73, v62, v63
	global_store_dwordx2 v[70:71], v[72:73], off offset:1536
	v_cvt_pk_bf16_f32 v62, v68, v69
	v_cvt_pk_bf16_f32 v63, v60, v61
	global_store_dwordx2 v[70:71], v[62:63], off offset:2048
	v_cvt_pk_bf16_f32 v60, v64, v65
	v_cvt_pk_bf16_f32 v61, v58, v59
	global_store_dwordx2 v[70:71], v[60:61], off offset:2560
	v_cvt_pk_bf16_f32 v56, v56, v57
	v_cvt_pk_bf16_f32 v57, v52, v53
	global_store_dwordx2 v[70:71], v[56:57], off offset:3072
	v_cvt_pk_bf16_f32 v52, v66, v67
	v_cvt_pk_bf16_f32 v53, v54, v55
	global_store_dwordx2 v[70:71], v[52:53], off offset:3584
	v_lshl_add_u64 v[4:5], v[4:5], 0, s[34:35]
	v_lshl_add_u64 v[2:3], v[2:3], 0, s[36:37]
	s_waitcnt vmcnt(9)
	v_mov_b64_e32 v[86:87], v[22:23]
	v_mov_b64_e32 v[84:85], v[26:27]
	v_mov_b64_e32 v[82:83], v[30:31]
	v_mov_b64_e32 v[80:81], v[34:35]
	v_mov_b64_e32 v[72:73], v[38:39]
	v_mov_b64_e32 v[70:71], v[42:43]
	v_mov_b64_e32 v[68:69], v[46:47]
	v_mov_b64_e32 v[66:67], v[50:51]
	v_mov_b64_e32 v[74:75], v[20:21]
	v_mov_b64_e32 v[64:65], v[24:25]
	v_mov_b64_e32 v[62:63], v[28:29]
	v_mov_b64_e32 v[60:61], v[32:33]
	v_mov_b64_e32 v[58:59], v[36:37]
	v_mov_b64_e32 v[56:57], v[40:41]
	v_mov_b64_e32 v[54:55], v[44:45]
	v_mov_b64_e32 v[52:53], v[48:49]
	s_andn2_b64 exec, exec, s[30:31]
	s_cbranch_execz .LBB0_928

; __device__ __forceinline__ float bf_lo(unsigned w) { return __uint_as_float(w << 16); }
; __device__ __forceinline__ float bf_hi(unsigned w) { return __uint_as_float(w & 0xffff0000u); }
; template <int MODE>
; __device__ __forceinline__ void rowwise_phase(const float* xin, bf16_t* hb, const bf16_t* f, const float* gpost, float alpha, float* rsout, float* fout, int wg, int nwg, int row0, int rowend) {
;     ...
;         if (HASF) {
;             f32x4 fv[8]; float ss = 0.f;
; #pragma unroll
;             for (int j = 0; j < 8; ++j) { const u32x2 w = fw[j]; fv[j] = (f32x4){bf_lo(w.x), bf_hi(w.x), bf_lo(w.y), bf_hi(w.y)};
;                 ss += (fv[j][0] * fv[j][0] + fv[j][1] * fv[j][1]) + (fv[j][2] * fv[j][2] + fv[j][3] * fv[j][3]); }
;             ss = wave_sum(ss);
;             const float rs = alpha * __frsqrt_rn(ss * (1.0f / DM) + EPS);
; #pragma unroll
;             for (int j = 0; j < 8; ++j) { const f32x4 g = ((const f32x4*)gpost)[lane + 64 * j]; h[j] += fv[j] * g * rs; }
.LBB0_926:
	s_or_b64 exec, exec, s[38:39]
	v_lshlrev_b32_e32 v88, 16, v86
	v_and_b32_e32 v89, 0xffff0000, v86
	v_lshlrev_b32_e32 v86, 16, v87
	v_and_b32_e32 v87, 0xffff0000, v87
	v_lshlrev_b32_e32 v76, 16, v74
	v_and_b32_e32 v77, 0xffff0000, v74
	v_lshlrev_b32_e32 v78, 16, v75
	v_and_b32_e32 v79, 0xffff0000, v75
	v_lshlrev_b32_e32 v74, 16, v64
	v_and_b32_e32 v75, 0xffff0000, v64
	v_mul_f32_e32 v64, v87, v87
	v_pk_fma_f32 v[98:99], v[86:87], v[86:87], v[64:65] op_sel_hi:[1,1,0]
	v_lshlrev_b32_e32 v91, 16, v85
	v_lshlrev_b32_e32 v90, 16, v84
	v_and_b32_e32 v85, 0xffff0000, v85
	v_and_b32_e32 v84, 0xffff0000, v84
	v_mul_f32_e32 v64, v89, v89
	v_pk_mul_f32 v[92:93], v[84:85], v[84:85]
	v_lshlrev_b32_e32 v97, 16, v80
	v_pk_fma_f32 v[102:103], v[88:89], v[88:89], v[64:65] op_sel_hi:[1,1,0]
	v_pk_fma_f32 v[100:101], v[90:91], v[90:91], v[92:93]
	v_and_b32_e32 v95, 0xffff0000, v80
	v_mov_b32_e32 v96, v102
	v_mov_b32_e32 v112, v98
	v_mov_b32_e32 v113, v97
	v_and_b32_e32 v93, 0xffff0000, v82
	v_mul_f32_e32 v1, v95, v95
	v_pk_add_f32 v[98:99], v[102:103], v[98:99]
	v_pk_mul_f32 v[102:103], v[96:97], v[112:113]
	v_pk_add_f32 v[100:101], v[100:101], v[100:101] op_sel:[0,1] op_sel_hi:[1,0]
	v_lshlrev_b32_e32 v92, 16, v82
	v_lshlrev_b32_e32 v82, 16, v83
	v_and_b32_e32 v83, 0xffff0000, v83
	v_mov_b32_e32 v99, v103
	v_mov_b32_e32 v101, v1
	v_mul_f32_e32 v64, v93, v93
	v_lshlrev_b32_e32 v80, 16, v81
	v_and_b32_e32 v81, 0xffff0000, v81
	v_pk_add_f32 v[98:99], v[98:99], v[100:101]
	v_pk_fma_f32 v[100:101], v[92:93], v[92:93], v[64:65] op_sel_hi:[1,1,0]
	v_mul_f32_e32 v64, v83, v83
	v_mul_f32_e32 v94, v80, v80
	v_mul_f32_e32 v111, v81, v81
	v_pk_fma_f32 v[102:103], v[82:83], v[82:83], v[64:65] op_sel_hi:[1,1,0]
	v_mov_b32_e32 v101, v94
	v_mov_b32_e32 v103, v111
	v_pk_add_f32 v[100:101], v[100:101], v[102:103]
	v_pk_add_f32 v[102:103], v[98:99], v[100:101]
	v_lshlrev_b32_e32 v99, 16, v73
	v_lshlrev_b32_e32 v98, 16, v72
	v_and_b32_e32 v73, 0xffff0000, v73
	v_and_b32_e32 v72, 0xffff0000, v72
	v_pk_mul_f32 v[100:101], v[72:73], v[72:73]
	v_lshlrev_b32_e32 v140, 16, v68
	v_pk_fma_f32 v[100:101], v[98:99], v[98:99], v[100:101]
	v_and_b32_e32 v141, 0xffff0000, v68
	v_pk_add_f32 v[124:125], v[100:101], v[100:101] op_sel:[0,1] op_sel_hi:[1,0]
	v_lshlrev_b32_e32 v101, 16, v71
	v_lshlrev_b32_e32 v100, 16, v70
	v_and_b32_e32 v71, 0xffff0000, v71
	v_and_b32_e32 v70, 0xffff0000, v70
	v_pk_mul_f32 v[116:117], v[70:71], v[70:71]
	v_lshlrev_b32_e32 v142, 16, v69
	v_pk_fma_f32 v[128:129], v[100:101], v[100:101], v[116:117]
	v_and_b32_e32 v143, 0xffff0000, v69
	v_lshlrev_b32_e32 v145, 16, v66
	v_and_b32_e32 v147, 0xffff0000, v66
	v_lshlrev_b32_e32 v148, 16, v67
	v_and_b32_e32 v149, 0xffff0000, v67
	v_pk_add_f32 v[102:103], v[102:103], v[102:103] op_sel:[0,1] op_sel_hi:[1,0]
	v_mov_b32_e32 v126, v124
	v_mov_b32_e32 v144, v102
	v_mov_b32_e32 v127, v145
	v_mul_f32_e32 v1, v147, v147
	v_pk_add_f32 v[102:103], v[102:103], v[124:125]
	v_pk_mul_f32 v[130:131], v[144:145], v[126:127]
	v_pk_add_f32 v[128:129], v[128:129], v[128:129] op_sel:[0,1] op_sel_hi:[1,0]
	v_mov_b32_e32 v103, v131
	v_mov_b32_e32 v129, v1
	v_pk_add_f32 v[102:103], v[102:103], v[128:129]
	v_mul_f32_e32 v64, v141, v141
	v_pk_fma_f32 v[136:137], v[140:141], v[140:141], v[64:65] op_sel_hi:[1,1,0]
	v_mul_f32_e32 v64, v143, v143
	v_mul_f32_e32 v94, v148, v148
	v_mul_f32_e32 v96, v149, v149
	v_pk_fma_f32 v[138:139], v[142:143], v[142:143], v[64:65] op_sel_hi:[1,1,0]
	v_mov_b32_e32 v137, v94
	v_mov_b32_e32 v139, v96
	v_pk_add_f32 v[136:137], v[136:137], v[138:139]
	v_lshlrev_b32_e32 v162, 16, v52
	v_pk_add_f32 v[102:103], v[102:103], v[136:137]
	v_add_f32_e32 v1, v102, v103
	ds_bpermute_b32 v94, v105, v1
	v_and_b32_e32 v163, 0xffff0000, v52
	v_lshlrev_b32_e32 v164, 16, v53
	v_and_b32_e32 v165, 0xffff0000, v53
	v_lshlrev_b32_e32 v150, 16, v62
	s_waitcnt lgkmcnt(0)
	v_add_f32_e32 v1, v1, v94
	ds_bpermute_b32 v94, v106, v1
	v_and_b32_e32 v151, 0xffff0000, v62
	v_lshlrev_b32_e32 v64, 16, v65
	v_and_b32_e32 v65, 0xffff0000, v65
	v_lshlrev_b32_e32 v152, 16, v60
	s_waitcnt lgkmcnt(0)
	v_add_f32_e32 v1, v1, v94
	ds_bpermute_b32 v94, v107, v1
	v_and_b32_e32 v153, 0xffff0000, v60
	v_lshlrev_b32_e32 v62, 16, v63
	v_and_b32_e32 v63, 0xffff0000, v63
	v_lshlrev_b32_e32 v60, 16, v61
	s_waitcnt lgkmcnt(0)
	v_add_f32_e32 v1, v1, v94
	ds_bpermute_b32 v94, v108, v1
	v_and_b32_e32 v61, 0xffff0000, v61
	v_lshlrev_b32_e32 v154, 16, v58
	v_and_b32_e32 v155, 0xffff0000, v58
	v_lshlrev_b32_e32 v58, 16, v59
	s_waitcnt lgkmcnt(0)
	v_add_f32_e32 v1, v1, v94
	ds_bpermute_b32 v94, v109, v1
	v_and_b32_e32 v59, 0xffff0000, v59
	v_lshlrev_b32_e32 v156, 16, v56
	v_pk_mul_f32 v[52:53], v[168:169], v[88:89]
	v_pk_mul_f32 v[86:87], v[170:171], v[86:87]
	s_waitcnt lgkmcnt(0)
; __device__ __forceinline__ unsigned cvt_pk_bf16(float lo, float hi) { unsigned r; asm volatile("v_cvt_pk_bf16_f32 %0, %1, %2" : "=v"(r) : "v"(lo), "v"(hi)); return r; }
; template <int MODE>
; __device__ __forceinline__ void rowwise_phase(const float* xin, bf16_t* hb, const bf16_t* f, const float* gpost, float alpha, float* rsout, float* fout, int wg, int nwg, int row0, int rowend) {
;     ...
;             ss = wave_sum(ss);
;             const float rs = alpha * __frsqrt_rn(ss * (1.0f / DM) + EPS);
; #pragma unroll
;             for (int j = 0; j < 8; ++j) { const f32x4 g = ((const f32x4*)gpost)[lane + 64 * j]; h[j] += fv[j] * g * rs; }
;         }
;         if (MODE == 2) {
;             f32x4* op = (f32x4*)(fout + (size_t)row * DM) + lane;
; #pragma unroll
;             for (int j = 0; j < 8; ++j) op[64 * j] = h[j];
;         } else {
;             float s2 = 0.f;
; #pragma unroll
;             for (int j = 0; j < 8; ++j) s2 += (h[j][0] * h[j][0] + h[j][1] * h[j][1]) + (h[j][2] * h[j][2] + h[j][3] * h[j][3]);
;             s2 = wave_sum(s2);
;             if (lane == 0) rsout[row] = __frsqrt_rn(s2 * (1.0f / DM) + EPS);
;             u32x2* up = (u32x2*)(hb + (size_t)row * DM) + lane;
; #pragma unroll
;             for (int j = 0; j < 8; ++j) { u32x2 w; w.x = cvt_pk_bf16(h[j][0], h[j][1]); w.y = cvt_pk_bf16(h[j][2], h[j][3]); up[64 * j] = w; }
	v_add_f32_e32 v1, v1, v94
	ds_bpermute_b32 v94, v110, v1
	v_and_b32_e32 v157, 0xffff0000, v56
	v_lshlrev_b32_e32 v56, 16, v57
	v_and_b32_e32 v57, 0xffff0000, v57
	v_lshlrev_b32_e32 v160, 16, v54
	s_waitcnt lgkmcnt(0)
	v_add_f32_e32 v1, v1, v94
	v_fmamk_f32 v1, v1, 0x3a000000, v104
	v_rsq_f32_e32 v1, v1
	v_mov_b32_e32 v94, v97
	v_and_b32_e32 v161, 0xffff0000, v54
	v_lshlrev_b32_e32 v54, 16, v55
	v_mul_f32_e32 v96, 0.5, v1
	v_pk_fma_f32 v[102:103], v[52:53], v[96:97], v[76:77] op_sel_hi:[1,0,1]
	v_mov_b32_e32 v52, v90
	v_mov_b32_e32 v53, v84
	v_pk_mul_f32 v[52:53], v[172:173], v[52:53]
	v_pk_fma_f32 v[88:89], v[86:87], v[96:97], v[78:79] op_sel_hi:[1,0,1]
	v_mov_b32_e32 v84, v91
	v_pk_fma_f32 v[86:87], v[52:53], v[96:97], v[74:75] op_sel_hi:[1,0,1]
	v_pk_mul_f32 v[76:77], v[174:175], v[84:85]
	v_mul_f32_e32 v1, v103, v103
	v_pk_mul_f32 v[52:53], v[176:177], v[92:93]
	v_pk_fma_f32 v[84:85], v[76:77], v[96:97], v[64:65] op_sel_hi:[1,0,1]
	v_pk_fma_f32 v[78:79], v[52:53], v[96:97], v[150:151] op_sel_hi:[1,0,1]
	v_pk_mul_f32 v[52:53], v[94:95], v[180:181]
	v_pk_mul_f32 v[64:65], v[178:179], v[82:83]
	v_pk_fma_f32 v[76:77], v[52:53], v[96:97], v[152:153] op_sel_hi:[1,0,1]
	v_mov_b32_e32 v52, v98
	v_mov_b32_e32 v53, v72
	v_pk_fma_f32 v[74:75], v[64:65], v[96:97], v[62:63] op_sel_hi:[1,0,1]
	v_pk_mul_f32 v[62:63], v[80:81], v[182:183]
	v_pk_mul_f32 v[52:53], v[184:185], v[52:53]
	v_mov_b32_e32 v72, v99
	v_pk_fma_f32 v[62:63], v[62:63], v[96:97], v[60:61] op_sel_hi:[1,0,1]
	v_pk_mul_f32 v[60:61], v[186:187], v[72:73]
	v_pk_fma_f32 v[68:69], v[52:53], v[96:97], v[154:155] op_sel_hi:[1,0,1]
	v_mov_b32_e32 v53, v70
	v_mov_b32_e32 v70, v101
	v_pk_fma_f32 v[60:61], v[60:61], v[96:97], v[58:59] op_sel_hi:[1,0,1]
	v_pk_mul_f32 v[58:59], v[190:191], v[70:71]
	v_mul_f32_e32 v70, v89, v89
	v_fmac_f32_e32 v1, v102, v102
	v_fmac_f32_e32 v70, v88, v88
	v_add_f32_e32 v1, v1, v70
	v_mul_f32_e32 v70, v87, v87
	v_mul_f32_e32 v71, v85, v85
	v_fmac_f32_e32 v70, v86, v86
	v_fmac_f32_e32 v71, v84, v84
	v_add_f32_e32 v70, v70, v71
	v_add_f32_e32 v1, v1, v70
	v_mul_f32_e32 v70, v79, v79
	v_mul_f32_e32 v71, v75, v75
	v_fmac_f32_e32 v70, v78, v78
	v_fmac_f32_e32 v71, v74, v74
	v_add_f32_e32 v70, v70, v71
	v_add_f32_e32 v1, v70, v1
	v_mul_f32_e32 v70, v77, v77
	v_mul_f32_e32 v71, v63, v63
	v_fmac_f32_e32 v70, v76, v76
	v_fmac_f32_e32 v71, v62, v62
	v_add_f32_e32 v70, v70, v71
	v_mov_b32_e32 v52, v100
	v_add_f32_e32 v1, v70, v1
	v_mul_f32_e32 v70, v69, v69
	v_mul_f32_e32 v71, v61, v61
	v_pk_mul_f32 v[52:53], v[188:189], v[52:53]
	v_fmac_f32_e32 v70, v68, v68
	v_fmac_f32_e32 v71, v60, v60
	v_pk_fma_f32 v[58:59], v[58:59], v[96:97], v[56:57] op_sel_hi:[1,0,1]
	v_pk_fma_f32 v[64:65], v[52:53], v[96:97], v[156:157] op_sel_hi:[1,0,1]
	v_add_f32_e32 v70, v70, v71
	v_add_f32_e32 v1, v70, v1
	v_mul_f32_e32 v70, v65, v65
	v_mul_f32_e32 v71, v59, v59
	v_and_b32_e32 v55, 0xffff0000, v55
	v_pk_mul_f32 v[56:57], v[192:193], v[140:141]
	v_pk_mul_f32 v[52:53], v[194:195], v[142:143]
	v_fmac_f32_e32 v70, v64, v64
	v_fmac_f32_e32 v71, v58, v58
	v_pk_fma_f32 v[52:53], v[96:97], v[52:53], v[54:55] op_sel_hi:[0,1,1]
	v_pk_fma_f32 v[56:57], v[96:97], v[56:57], v[160:161] op_sel_hi:[0,1,1]
	v_add_f32_e32 v70, v70, v71
	v_mov_b32_e32 v146, v145
	v_add_f32_e32 v1, v70, v1
	v_mul_f32_e32 v70, v57, v57
	v_mul_f32_e32 v71, v53, v53
	v_pk_mul_f32 v[66:67], v[146:147], v[196:197]
	v_pk_mul_f32 v[54:55], v[148:149], v[198:199]
	v_fmac_f32_e32 v70, v56, v56
	v_fmac_f32_e32 v71, v52, v52
	v_pk_fma_f32 v[54:55], v[96:97], v[54:55], v[164:165] op_sel_hi:[0,1,1]
	v_pk_fma_f32 v[66:67], v[96:97], v[66:67], v[162:163] op_sel_hi:[0,1,1]
	v_add_f32_e32 v70, v70, v71
	v_add_f32_e32 v1, v70, v1
	v_mul_f32_e32 v70, v67, v67
	v_mul_f32_e32 v71, v55, v55
	v_fmac_f32_e32 v70, v66, v66
	v_fmac_f32_e32 v71, v54, v54
	v_add_f32_e32 v70, v70, v71
	v_add_f32_e32 v1, v70, v1
	ds_bpermute_b32 v70, v105, v1
	s_waitcnt lgkmcnt(0)
	v_add_f32_e32 v1, v1, v70
	ds_bpermute_b32 v70, v106, v1
	s_waitcnt lgkmcnt(0)
	v_add_f32_e32 v1, v1, v70
	ds_bpermute_b32 v70, v107, v1
	s_waitcnt lgkmcnt(0)
	v_add_f32_e32 v1, v1, v70
	ds_bpermute_b32 v70, v108, v1
	s_waitcnt lgkmcnt(0)
	v_add_f32_e32 v1, v1, v70
	ds_bpermute_b32 v70, v109, v1
	s_waitcnt lgkmcnt(0)
	v_add_f32_e32 v1, v1, v70
	ds_bpermute_b32 v70, v110, v1
	s_and_saveexec_b64 s[2:3], s[6:7]
	s_cbranch_execz .LBB0_923
	s_waitcnt lgkmcnt(0)
	v_add_f32_e32 v1, v1, v70
	v_fmamk_f32 v1, v1, 0x3a000000, v104
	v_rsq_f32_e32 v1, v1
	v_lshl_add_u64 v[70:71], s[16:17], 0, v[4:5]
	global_store_dword v[70:71], v1, off
	s_branch .LBB0_923

; __device__ __forceinline__ float bf_lo(unsigned w) { return __uint_as_float(w << 16); }
; __device__ __forceinline__ float bf_hi(unsigned w) { return __uint_as_float(w & 0xffff0000u); }
; __device__ __forceinline__ int fresh_tid() { int t = threadIdx.x; asm volatile("" : "+v"(t)); return t; }
; template <int MODE>
; __device__ __forceinline__ void rowwise_phase(const float* xin, bf16_t* hb, const bf16_t* f, const float* gpost, float alpha, float* rsout, float* fout, int wg, int nwg, int row0, int rowend) {
;     const int tid = fresh_tid(), lane = tid & 63, gw = row0 + wg * 8 + (tid >> 6), NGW = nwg * 8;
;     constexpr bool XIN = (MODE == 0 || MODE == 1), HASF = (MODE != 0);
;     f32x4 xN[8]; u32x2 hN[8], fN[8];
;     ...
;     if (gw < rowend) ROW_LOAD(gw);
;     for (int row = gw; row < rowend; row += NGW) {
;         f32x4 h[8]; u32x2 fw[8];
; #pragma unroll
;         for (int j = 0; j < 8; ++j) { if (XIN) h[j] = xN[j]; else h[j] = (f32x4){bf_lo(hN[j].x), bf_hi(hN[j].x), bf_lo(hN[j].y), bf_hi(hN[j].y)}; if (HASF) fw[j] = fN[j]; }
;         const int nrow = row + NGW;
;         if (nrow < rowend) ROW_LOAD(nrow);
;     ...
;             for (int j = 0; j < 8; ++j) { const f32x4 g = ((const f32x4*)gpost)[lane + 64 * j]; h[j] += fv[j] * g * rs; }
.LBB0_1056:
	s_or_b64 exec, exec, s[2:3]
	s_waitcnt lgkmcnt(0)
	s_barrier
	v_readlane_b32 s2, v232, 23
	v_ashrrev_i32_e32 v14, 6, v158
	s_nop 0
	v_add_u32_e32 v0, s2, v14
	v_cmp_gt_i32_e32 vcc, s13, v0
	s_and_saveexec_b64 s[2:3], vcc
	s_cbranch_execz .LBB0_1061
	v_ashrrev_i32_e32 v1, 31, v0
	v_readlane_b32 s2, v232, 7
	v_lshlrev_b64 v[2:3], 12, v[0:1]
	v_readlane_b32 s3, v232, 8
	v_and_b32_e32 v6, 63, v158
	v_lshlrev_b32_e32 v16, 3, v6
	v_lshl_add_u64 v[4:5], s[2:3], 0, v[2:3]
	v_readlane_b32 s2, v232, 16
	v_readlane_b32 s3, v232, 17
	v_mov_b32_e32 v17, 0
	v_lshl_add_u64 v[4:5], v[4:5], 0, v[16:17]
	v_lshl_add_u64 v[2:3], s[2:3], 0, v[2:3]
	v_lshl_add_u64 v[2:3], v[2:3], 0, v[16:17]
	global_load_dwordx2 v[82:83], v[2:3], off
	global_load_dwordx2 v[86:87], v[2:3], off offset:512
	global_load_dwordx2 v[80:81], v[2:3], off offset:1024
	global_load_dwordx2 v[76:77], v[2:3], off offset:1536
	global_load_dwordx2 v[70:71], v[2:3], off offset:2048
	global_load_dwordx2 v[66:67], v[2:3], off offset:2560
	global_load_dwordx2 v[64:65], v[2:3], off offset:3072
	global_load_dwordx2 v[62:63], v[2:3], off offset:3584
	global_load_dwordx2 v[68:69], v[4:5], off
	global_load_dwordx2 v[60:61], v[4:5], off offset:512
	global_load_dwordx2 v[58:59], v[4:5], off offset:1024
	global_load_dwordx2 v[56:57], v[4:5], off offset:1536
	global_load_dwordx2 v[54:55], v[4:5], off offset:2048
	global_load_dwordx2 v[52:53], v[4:5], off offset:2560
	global_load_dwordx2 v[50:51], v[4:5], off offset:3072
	global_load_dwordx2 v[48:49], v[4:5], off offset:3584
	v_mbcnt_hi_u32_b32 v2, -1, v159
	v_and_b32_e32 v3, 64, v2
	v_add_u32_e32 v3, 64, v3
	v_xor_b32_e32 v4, 1, v2
	v_cmp_lt_i32_e32 vcc, v4, v3
	s_load_dwordx2 s[0:1], s[0:1], 0xa8
	v_lshlrev_b32_e32 v12, 4, v6
	v_cndmask_b32_e32 v4, v2, v4, vcc
	v_lshlrev_b32_e32 v98, 2, v4
	v_xor_b32_e32 v4, 2, v2
	v_cmp_lt_i32_e32 vcc, v4, v3
	v_mov_b32_e32 v13, v17
	s_mov_b64 s[2:3], 0x1400
	v_cndmask_b32_e32 v4, v2, v4, vcc
	v_lshlrev_b32_e32 v99, 2, v4
	v_xor_b32_e32 v4, 4, v2
	v_cmp_lt_i32_e32 vcc, v4, v3
	v_lshlrev_b64 v[18:19], 13, v[0:1]
	v_or_b32_e32 v18, v18, v12
	v_cndmask_b32_e32 v4, v2, v4, vcc
	v_lshlrev_b32_e32 v100, 2, v4
	v_xor_b32_e32 v4, 8, v2
	v_cmp_lt_i32_e32 vcc, v4, v3
	s_ashr_i32 s27, s26, 31
	s_lshl_b64 s[4:5], s[26:27], 12
	v_cndmask_b32_e32 v4, v2, v4, vcc
	v_lshlrev_b32_e32 v101, 2, v4
	v_xor_b32_e32 v4, 16, v2
	v_cmp_lt_i32_e32 vcc, v4, v3
	s_mov_b64 s[6:7], 0
	v_mov_b32_e32 v1, 0x358637bd
	v_cndmask_b32_e32 v4, v2, v4, vcc
	v_lshlrev_b32_e32 v102, 2, v4
	v_xor_b32_e32 v4, 32, v2
	v_cmp_lt_i32_e32 vcc, v4, v3
	s_waitcnt vmcnt(15)
	v_mov_b64_e32 v[22:23], v[82:83]
	v_cndmask_b32_e32 v2, v2, v4, vcc
	v_lshlrev_b32_e32 v103, 2, v2
	s_waitcnt lgkmcnt(0)
	v_lshl_add_u64 v[2:3], s[0:1], 0, v[12:13]
	v_lshl_add_u64 v[6:7], v[2:3], 0, s[2:3]
	s_mov_b64 s[2:3], 0x1800
	v_lshl_add_u64 v[8:9], v[2:3], 0, s[2:3]
	s_mov_b64 s[2:3], 0x1c00
	v_lshl_add_u64 v[10:11], v[2:3], 0, s[2:3]
	v_readlane_b32 s2, v232, 24
	v_readlane_b32 s3, v232, 25
	s_mov_b64 s[0:1], 0x1000
	v_lshl_add_u64 v[4:5], v[2:3], 0, s[0:1]
	v_lshl_add_u64 v[12:13], s[2:3], 0, v[18:19]
	v_lshl_add_u64 v[12:13], v[12:13], 0, s[0:1]
	v_readlane_b32 s0, v232, 22
	s_add_i32 s0, s26, s0
	s_add_i32 s0, s0, s61
	v_readlane_b32 s1, v232, 6
	s_add_i32 s0, s0, s1
	v_add_u32_e32 v14, s0, v14
	v_ashrrev_i32_e32 v15, 31, v14
	v_lshlrev_b64 v[14:15], 12, v[14:15]
	v_or_b32_e32 v14, v14, v16
	v_lshl_add_u64 v[14:15], s[16:17], 0, v[14:15]
	s_mov_b64 s[0:1], 0xbb50000
	s_lshl_b64 s[2:3], s[26:27], 13
	v_lshl_add_u64 v[14:15], v[14:15], 0, s[0:1]
	s_waitcnt vmcnt(14)
	v_mov_b64_e32 v[26:27], v[86:87]
	s_waitcnt vmcnt(13)
	v_mov_b64_e32 v[30:31], v[80:81]
	s_waitcnt vmcnt(12)
	v_mov_b64_e32 v[34:35], v[76:77]
	s_waitcnt vmcnt(11)
	v_mov_b64_e32 v[38:39], v[70:71]
	s_waitcnt vmcnt(10)
	v_mov_b64_e32 v[42:43], v[66:67]
	s_waitcnt vmcnt(9)
	v_mov_b64_e32 v[44:45], v[64:65]
	s_waitcnt vmcnt(8)
	v_mov_b64_e32 v[46:47], v[62:63]
	s_waitcnt vmcnt(7)
	v_mov_b64_e32 v[16:17], v[68:69]
	s_waitcnt vmcnt(6)
	v_mov_b64_e32 v[18:19], v[60:61]
	s_waitcnt vmcnt(5)
	v_mov_b64_e32 v[20:21], v[58:59]
	s_waitcnt vmcnt(4)
	v_mov_b64_e32 v[24:25], v[56:57]
	s_waitcnt vmcnt(3)
	v_mov_b64_e32 v[28:29], v[54:55]
	s_waitcnt vmcnt(2)
	v_mov_b64_e32 v[32:33], v[52:53]
	s_waitcnt vmcnt(1)
	v_mov_b64_e32 v[36:37], v[50:51]
	s_waitcnt vmcnt(0)
	v_mov_b64_e32 v[40:41], v[48:49]
	global_load_dwordx4 v[168:171], v[2:3], off
	global_load_dwordx4 v[172:175], v[2:3], off offset:1024
	global_load_dwordx4 v[176:179], v[2:3], off offset:2048
	global_load_dwordx4 v[180:183], v[2:3], off offset:3072
	global_load_dwordx4 v[184:187], v[4:5], off
	global_load_dwordx4 v[188:191], v[6:7], off
	global_load_dwordx4 v[192:195], v[8:9], off
	global_load_dwordx4 v[196:199], v[10:11], off
	s_waitcnt vmcnt(0)
	s_branch .LBB0_1059
; __device__ __forceinline__ float bf_lo(unsigned w) { return __uint_as_float(w << 16); }
; __device__ __forceinline__ float bf_hi(unsigned w) { return __uint_as_float(w & 0xffff0000u); }
; template <int MODE>
; __device__ __forceinline__ void rowwise_phase(const float* xin, bf16_t* hb, const bf16_t* f, const float* gpost, float alpha, float* rsout, float* fout, int wg, int nwg, int row0, int rowend) {
;     ...
;         if (HASF) {
;             f32x4 fv[8]; float ss = 0.f;
; #pragma unroll
;             for (int j = 0; j < 8; ++j) { const u32x2 w = fw[j]; fv[j] = (f32x4){bf_lo(w.x), bf_hi(w.x), bf_lo(w.y), bf_hi(w.y)};
;                 ss += (fv[j][0] * fv[j][0] + fv[j][1] * fv[j][1]) + (fv[j][2] * fv[j][2] + fv[j][3] * fv[j][3]); }
;             ss = wave_sum(ss);
;             const float rs = alpha * __frsqrt_rn(ss * (1.0f / DM) + EPS);
; #pragma unroll
;             for (int j = 0; j < 8; ++j) { const f32x4 g = ((const f32x4*)gpost)[lane + 64 * j]; h[j] += fv[j] * g * rs; }
.LBB0_1058:
	s_or_b64 exec, exec, s[8:9]
	v_lshlrev_b32_e32 v78, 16, v82
	v_and_b32_e32 v79, 0xffff0000, v82
	v_lshlrev_b32_e32 v82, 16, v83
	v_and_b32_e32 v83, 0xffff0000, v83
	v_mul_f32_e32 v84, v83, v83
	v_pk_fma_f32 v[94:95], v[82:83], v[82:83], v[84:85] op_sel_hi:[1,1,0]
	v_lshlrev_b32_e32 v85, 16, v87
	v_lshlrev_b32_e32 v84, 16, v86
	v_and_b32_e32 v87, 0xffff0000, v87
	v_and_b32_e32 v86, 0xffff0000, v86
	v_and_b32_e32 v91, 0xffff0000, v76
	v_mul_f32_e32 v90, v79, v79
	v_pk_mul_f32 v[88:89], v[86:87], v[86:87]
	v_lshlrev_b32_e32 v93, 16, v76
	v_pk_fma_f32 v[104:105], v[78:79], v[78:79], v[90:91] op_sel_hi:[1,1,0]
	v_pk_fma_f32 v[96:97], v[84:85], v[84:85], v[88:89]
	v_mov_b32_e32 v92, v104
	v_mov_b32_e32 v106, v94
	v_mov_b32_e32 v107, v93
	v_and_b32_e32 v89, 0xffff0000, v80
	v_mul_f32_e32 v108, v91, v91
	v_pk_add_f32 v[94:95], v[104:105], v[94:95]
	v_pk_mul_f32 v[104:105], v[92:93], v[106:107]
	v_pk_add_f32 v[96:97], v[96:97], v[96:97] op_sel:[0,1] op_sel_hi:[1,0]
	v_lshlrev_b32_e32 v88, 16, v80
	v_lshlrev_b32_e32 v80, 16, v81
	v_and_b32_e32 v81, 0xffff0000, v81
	v_mov_b32_e32 v95, v105
	v_mov_b32_e32 v97, v108
	v_mul_f32_e32 v90, v89, v89
	v_lshlrev_b32_e32 v76, 16, v77
	v_and_b32_e32 v77, 0xffff0000, v77
	v_pk_add_f32 v[94:95], v[94:95], v[96:97]
	v_pk_fma_f32 v[96:97], v[88:89], v[88:89], v[90:91] op_sel_hi:[1,1,0]
	v_mul_f32_e32 v90, v81, v81
	v_mul_f32_e32 v109, v76, v76
	v_mul_f32_e32 v110, v77, v77
	v_pk_fma_f32 v[104:105], v[80:81], v[80:81], v[90:91] op_sel_hi:[1,1,0]
	v_mov_b32_e32 v97, v109
	v_mov_b32_e32 v105, v110
	v_pk_add_f32 v[96:97], v[96:97], v[104:105]
	v_and_b32_e32 v139, 0xffff0000, v62
	v_pk_add_f32 v[116:117], v[94:95], v[96:97]
	v_lshlrev_b32_e32 v95, 16, v71
	v_lshlrev_b32_e32 v94, 16, v70
	v_and_b32_e32 v71, 0xffff0000, v71
	v_and_b32_e32 v70, 0xffff0000, v70
	v_pk_mul_f32 v[96:97], v[70:71], v[70:71]
	v_and_b32_e32 v133, 0xffff0000, v64
	v_pk_fma_f32 v[96:97], v[94:95], v[94:95], v[96:97]
	v_mul_f32_e32 v90, v139, v139
	v_pk_add_f32 v[120:121], v[96:97], v[96:97] op_sel:[0,1] op_sel_hi:[1,0]
	v_lshlrev_b32_e32 v97, 16, v67
	v_lshlrev_b32_e32 v96, 16, v66
	v_and_b32_e32 v67, 0xffff0000, v67
	v_and_b32_e32 v66, 0xffff0000, v66
	v_pk_mul_f32 v[108:109], v[66:67], v[66:67]
	v_pk_fma_f32 v[122:123], v[96:97], v[96:97], v[108:109]
	v_lshlrev_b32_e32 v132, 16, v64
	v_pk_add_f32 v[122:123], v[122:123], v[122:123] op_sel:[0,1] op_sel_hi:[1,0]
	v_and_b32_e32 v135, 0xffff0000, v65
	v_lshlrev_b32_e32 v137, 16, v62
	v_pk_add_f32 v[124:125], v[116:117], v[116:117] op_sel:[0,1] op_sel_hi:[1,0]
	v_mov_b32_e32 v123, v90
	v_mul_f32_e32 v90, v133, v133
	v_lshlrev_b32_e32 v134, 16, v65
	v_lshlrev_b32_e32 v140, 16, v63
	v_and_b32_e32 v141, 0xffff0000, v63
	v_mov_b32_e32 v136, v124
	v_mov_b32_e32 v126, v120
	v_mov_b32_e32 v127, v137
	v_pk_fma_f32 v[130:131], v[132:133], v[132:133], v[90:91] op_sel_hi:[1,1,0]
	v_mul_f32_e32 v90, v135, v135
	v_mul_f32_e32 v92, v140, v140
	v_mul_f32_e32 v138, v141, v141
	v_pk_add_f32 v[120:121], v[124:125], v[120:121]
	v_pk_mul_f32 v[124:125], v[136:137], v[126:127]
	v_pk_fma_f32 v[142:143], v[134:135], v[134:135], v[90:91] op_sel_hi:[1,1,0]
	v_mov_b32_e32 v121, v125
	v_mov_b32_e32 v131, v92
	v_mov_b32_e32 v143, v138
	v_pk_add_f32 v[128:129], v[120:121], v[122:123]
	v_pk_add_f32 v[130:131], v[130:131], v[142:143]
	v_pk_add_f32 v[142:143], v[128:129], v[130:131]
	v_add_f32_e32 v90, v142, v143
	ds_bpermute_b32 v92, v98, v90
	v_lshlrev_b32_e32 v144, 16, v56
	v_and_b32_e32 v145, 0xffff0000, v56
	v_lshlrev_b32_e32 v148, 16, v54
	v_and_b32_e32 v149, 0xffff0000, v54
	s_waitcnt lgkmcnt(0)
	v_add_f32_e32 v90, v90, v92
	ds_bpermute_b32 v92, v99, v90
	v_lshlrev_b32_e32 v152, 16, v52
	v_and_b32_e32 v153, 0xffff0000, v52
	v_lshlrev_b32_e32 v156, 16, v50
	v_and_b32_e32 v157, 0xffff0000, v50
	s_waitcnt lgkmcnt(0)
	v_add_f32_e32 v56, v90, v92
	ds_bpermute_b32 v90, v100, v56
	v_lshlrev_b32_e32 v160, 16, v48
	v_and_b32_e32 v161, 0xffff0000, v48
	v_lshlrev_b32_e32 v154, 16, v53
	v_and_b32_e32 v155, 0xffff0000, v53
	s_waitcnt lgkmcnt(0)
	v_add_f32_e32 v54, v56, v90
	ds_bpermute_b32 v56, v101, v54
	v_mov_b32_e32 v53, v86
	v_mov_b32_e32 v86, v85
	v_lshlrev_b32_e32 v72, 16, v68
	v_and_b32_e32 v73, 0xffff0000, v68
	s_waitcnt lgkmcnt(0)
; __device__ __forceinline__ float bf_lo(unsigned w) { return __uint_as_float(w << 16); }
; __device__ __forceinline__ float bf_hi(unsigned w) { return __uint_as_float(w & 0xffff0000u); }
; template <int MODE>
; __device__ __forceinline__ void rowwise_phase(const float* xin, bf16_t* hb, const bf16_t* f, const float* gpost, float alpha, float* rsout, float* fout, int wg, int nwg, int row0, int rowend) {
;     ...
;     for (int row = gw; row < rowend; row += NGW) {
;         f32x4 h[8]; u32x2 fw[8];
; #pragma unroll
;         for (int j = 0; j < 8; ++j) { if (XIN) h[j] = xN[j]; else h[j] = (f32x4){bf_lo(hN[j].x), bf_hi(hN[j].x), bf_lo(hN[j].y), bf_hi(hN[j].y)}; if (HASF) fw[j] = fN[j]; }
;         const int nrow = row + NGW;
;         if (nrow < rowend) ROW_LOAD(nrow);
;     ...
;             const float rs = alpha * __frsqrt_rn(ss * (1.0f / DM) + EPS);
; #pragma unroll
;             for (int j = 0; j < 8; ++j) { const f32x4 g = ((const f32x4*)gpost)[lane + 64 * j]; h[j] += fv[j] * g * rs; }
;         }
;         if (MODE == 2) {
;             f32x4* op = (f32x4*)(fout + (size_t)row * DM) + lane;
; #pragma unroll
;             for (int j = 0; j < 8; ++j) op[64 * j] = h[j];
	v_add_f32_e32 v52, v54, v56
	ds_bpermute_b32 v54, v102, v52
	v_lshlrev_b32_e32 v74, 16, v69
	v_and_b32_e32 v75, 0xffff0000, v69
	v_lshlrev_b32_e32 v68, 16, v60
	v_and_b32_e32 v69, 0xffff0000, v60
	s_waitcnt lgkmcnt(0)
	v_add_f32_e32 v50, v52, v54
	ds_bpermute_b32 v52, v103, v50
	v_lshlrev_b32_e32 v60, 16, v61
	v_and_b32_e32 v61, 0xffff0000, v61
	v_lshlrev_b32_e32 v150, 16, v55
	v_and_b32_e32 v151, 0xffff0000, v55
	s_waitcnt lgkmcnt(0)
	v_add_f32_e32 v48, v50, v52
	v_fmamk_f32 v48, v48, 0x3a000000, v1
	v_rsq_f32_e32 v92, v48
	v_lshlrev_b32_e32 v142, 16, v58
	v_and_b32_e32 v143, 0xffff0000, v58
	v_lshlrev_b32_e32 v58, 16, v59
	v_and_b32_e32 v59, 0xffff0000, v59
	v_mov_b32_e32 v52, v84
	v_mov_b32_e32 v90, v93
	v_mov_b32_e32 v138, v137
	v_lshlrev_b32_e32 v146, 16, v57
	v_and_b32_e32 v147, 0xffff0000, v57
	v_lshlrev_b32_e32 v158, 16, v51
	v_pk_mul_f32 v[54:55], v[174:175], v[86:87]
	v_pk_mul_f32 v[52:53], v[172:173], v[52:53]
	v_pk_fma_f32 v[54:55], v[54:55], v[92:93], v[60:61] op_sel_hi:[1,0,1]
	v_pk_fma_f32 v[52:53], v[52:53], v[92:93], v[68:69] op_sel_hi:[1,0,1]
	v_and_b32_e32 v159, 0xffff0000, v51
	v_lshlrev_b32_e32 v162, 16, v49
	v_and_b32_e32 v163, 0xffff0000, v49
	v_pk_mul_f32 v[60:61], v[178:179], v[80:81]
	v_pk_mul_f32 v[48:49], v[168:169], v[78:79]
	v_pk_fma_f32 v[58:59], v[60:61], v[92:93], v[58:59] op_sel_hi:[1,0,1]
	v_pk_mul_f32 v[50:51], v[170:171], v[82:83]
	v_pk_mul_f32 v[56:57], v[176:177], v[88:89]
	s_and_b64 s[0:1], exec, s[0:1]
	v_pk_fma_f32 v[50:51], v[50:51], v[92:93], v[74:75] op_sel_hi:[1,0,1]
	v_pk_fma_f32 v[48:49], v[48:49], v[92:93], v[72:73] op_sel_hi:[1,0,1]
	v_pk_fma_f32 v[56:57], v[56:57], v[92:93], v[142:143] op_sel_hi:[1,0,1]
	v_pk_mul_f32 v[60:61], v[90:91], v[180:181]
	v_pk_mul_f32 v[62:63], v[76:77], v[182:183]
	v_mov_b32_e32 v64, v94
	v_mov_b32_e32 v65, v70
	v_mov_b32_e32 v70, v95
	v_pk_mul_f32 v[64:65], v[184:185], v[64:65]
	v_pk_mul_f32 v[68:69], v[186:187], v[70:71]
	v_pk_fma_f32 v[62:63], v[62:63], v[92:93], v[146:147] op_sel_hi:[1,0,1]
	v_pk_fma_f32 v[70:71], v[68:69], v[92:93], v[150:151] op_sel_hi:[1,0,1]
	v_pk_fma_f32 v[68:69], v[64:65], v[92:93], v[148:149] op_sel_hi:[1,0,1]
	v_mov_b32_e32 v64, v96
	v_mov_b32_e32 v65, v66
	v_mov_b32_e32 v66, v97
	v_pk_mul_f32 v[64:65], v[188:189], v[64:65]
	v_pk_mul_f32 v[66:67], v[190:191], v[66:67]
	v_pk_mul_f32 v[76:77], v[138:139], v[196:197]
	v_pk_fma_f32 v[60:61], v[60:61], v[92:93], v[144:145] op_sel_hi:[1,0,1]
	v_pk_fma_f32 v[66:67], v[92:93], v[66:67], v[154:155] op_sel_hi:[0,1,1]
	v_pk_fma_f32 v[64:65], v[92:93], v[64:65], v[152:153] op_sel_hi:[0,1,1]
	v_pk_mul_f32 v[72:73], v[192:193], v[132:133]
	v_pk_mul_f32 v[74:75], v[194:195], v[134:135]
	v_pk_mul_f32 v[78:79], v[140:141], v[198:199]
	v_pk_fma_f32 v[76:77], v[92:93], v[76:77], v[160:161] op_sel_hi:[0,1,1]
	s_or_b64 s[6:7], s[0:1], s[6:7]
	v_pk_fma_f32 v[74:75], v[92:93], v[74:75], v[158:159] op_sel_hi:[0,1,1]
	v_pk_fma_f32 v[72:73], v[92:93], v[72:73], v[156:157] op_sel_hi:[0,1,1]
	v_pk_fma_f32 v[78:79], v[92:93], v[78:79], v[162:163] op_sel_hi:[0,1,1]
	global_store_dwordx4 v[12:13], v[48:51], off offset:-4096
	global_store_dwordx4 v[12:13], v[52:55], off offset:-3072
	global_store_dwordx4 v[12:13], v[56:59], off offset:-2048
	global_store_dwordx4 v[12:13], v[60:63], off offset:-1024
	global_store_dwordx4 v[12:13], v[68:71], off
	global_store_dwordx4 v[12:13], v[64:67], off offset:1024
	global_store_dwordx4 v[12:13], v[72:75], off offset:2048
	global_store_dwordx4 v[12:13], v[76:79], off offset:3072
	v_lshl_add_u64 v[12:13], v[12:13], 0, s[2:3]
	v_lshl_add_u64 v[14:15], v[14:15], 0, s[4:5]
	s_waitcnt vmcnt(8)
	v_mov_b64_e32 v[82:83], v[22:23]
	v_mov_b64_e32 v[86:87], v[26:27]
	v_mov_b64_e32 v[80:81], v[30:31]
	v_mov_b64_e32 v[76:77], v[34:35]
	v_mov_b64_e32 v[70:71], v[38:39]
	v_mov_b64_e32 v[66:67], v[42:43]
	v_mov_b64_e32 v[64:65], v[44:45]
	v_mov_b64_e32 v[62:63], v[46:47]
	v_mov_b64_e32 v[68:69], v[16:17]
	v_mov_b64_e32 v[60:61], v[18:19]
	v_mov_b64_e32 v[58:59], v[20:21]
	v_mov_b64_e32 v[56:57], v[24:25]
	v_mov_b64_e32 v[54:55], v[28:29]
	v_mov_b64_e32 v[52:53], v[32:33]
	v_mov_b64_e32 v[50:51], v[36:37]
	v_mov_b64_e32 v[48:49], v[40:41]
	s_andn2_b64 exec, exec, s[6:7]
	s_cbranch_execz .LBB0_1061
